# RWKV step: LDS operand reads interleaved with the VALU stream
# baseline (speedup 1.0000x reference)
; DEVINL u16 f2bf(float a) { return (u16)(pk2(a, 0.f) & 0xffffu); }
; #define RW_STEP2(B) RW_STEP(B, WvA, XA, KrA, vhA, WvB, XB, KrB, vhB); RW_STEP((B) + 1, WvB, XB, KrB, vhB, WvA, XA, KrA, vhA)
; #define RW_STEP4(B) RW_STEP2(B); RW_STEP2((B) + 2)
; template <int DIR>
; DEVINL void rwkv_scan_dir(const Params& p, int task, int lane, int wave) {
;     ...
;   for (int st = 0; st < 4096; st += 32) {
;     RW_STEP(0, WvA, XA, KrA, vhA, WvB, XB, KrB, vhB);
;     if (st > 0) { const int q0 = st - 16 + seg; yo[(long)(DIR ? (4095 - q0) : q0) * 1024] = f2bf(ykeep); }
;     RW_STEP(1, WvB, XB, KrB, vhB, WvA, XA, KrA, vhA);
;     RW_STEP2(2); RW_STEP4(4); RW_STEP4(8); RW_STEP4(12);
;     RW_STEP(16, WvA, XA, KrA, vhA, WvB, XB, KrB, vhB);
;     { const int q0 = st + seg; yo[(long)(DIR ? (4095 - q0) : q0) * 1024] = f2bf(ykeep); }
.Lrw_ready_d0:
	s_add_u32 s3, s40, s41
	s_and_b32 s3, s3, 0x1ffff
	s_add_u32 s3, s3, 16
	s_mov_b32 m0, s3
	s_nop 0
	global_load_lds_dwordx4 v5, s[10:11] offset:0
	global_load_lds_dwordx4 v5, s[10:11] offset:1024
	global_load_lds_dwordx4 v5, s[10:11] offset:2048
	global_load_lds_dwordx4 v5, s[10:11] offset:3072
	s_add_u32 s10, s10, 0x4000
	s_addc_u32 s11, s11, 0
	s_add_u32 s41, s41, 0x4000
	s_and_b32 s41, s41, 0x1ffff
	ds_read_b64 v[72:73], v6 offset:2064
	v_fma_mix_f32 v14, v10, v26, 0 op_sel:[0,0,0] op_sel_hi:[0,1,0]
	v_fma_mix_f32 v63, v10, v92, 0 op_sel:[0,0,0] op_sel_hi:[0,1,0]
	v_fma_mix_f32 v14, v11, v26, v14 op_sel:[0,1,0] op_sel_hi:[0,1,0]
	ds_read_b128 v[74:77], v6 offset:2320
	v_fma_mix_f32 v63, v11, v92, v63 op_sel:[0,1,0] op_sel_hi:[0,1,0]
	v_fma_mix_f32 v14, v12, v27, v14 op_sel:[0,0,0] op_sel_hi:[0,1,0]
	v_fma_mix_f32 v63, v12, v93, v63 op_sel:[0,0,0] op_sel_hi:[0,1,0]
	ds_read_b128 v[78:81], v6 offset:2576
	v_fma_mix_f32 v14, v13, v27, v14 op_sel:[0,1,0] op_sel_hi:[0,1,0]
	v_fma_mix_f32 v16, v10, v24, 0 op_sel:[0,0,0] op_sel_hi:[0,1,0]
	v_fma_mix_f32 v17, v11, v24, 0 op_sel:[0,1,0] op_sel_hi:[0,1,0]
	ds_read_u16 v82, v7 offset:2064
	v_add_f32_dpp v20, v14, v14 quad_perm:[1,0,3,2] row_mask:0xf bank_mask:0xf bound_ctrl:1
	v_fma_mix_f32 v63, v13, v93, v63 op_sel:[0,1,0] op_sel_hi:[0,1,0]
	v_fma_mix_f32 v18, v12, v25, 0 op_sel:[0,0,0] op_sel_hi:[0,1,0]
	v_add_f32_dpp v20, v20, v20 quad_perm:[2,3,0,1] row_mask:0xf bank_mask:0xf bound_ctrl:1
	v_fma_mix_f32 v19, v13, v25, 0 op_sel:[0,1,0] op_sel_hi:[0,1,0]
	v_fma_mix_f32 v16, v34, v30, v16 op_sel:[0,0,0] op_sel_hi:[1,1,0]
	v_add_f32_dpp v20, v20, v20 row_half_mirror row_mask:0xf bank_mask:0xf bound_ctrl:1
	v_fma_mix_f32 v17, v34, v30, v17 op_sel:[0,1,0] op_sel_hi:[1,1,0]
	v_fma_mix_f32 v18, v34, v31, v18 op_sel:[0,0,0] op_sel_hi:[1,1,0]
	v_add_f32_dpp v20, v20, v20 row_mirror row_mask:0xf bank_mask:0xf bound_ctrl:1
	v_fma_mix_f32 v19, v34, v31, v19 op_sel:[0,1,0] op_sel_hi:[1,1,0]
	v_fma_mix_f32 v10, v20, v28, v16 op_sel:[0,0,0] op_sel_hi:[0,1,0]
	v_fma_mix_f32 v11, v20, v28, v17 op_sel:[0,1,0] op_sel_hi:[0,1,0]
	v_fma_mix_f32 v12, v20, v29, v18 op_sel:[0,0,0] op_sel_hi:[0,1,0]
	v_fma_mix_f32 v13, v20, v29, v19 op_sel:[0,1,0] op_sel_hi:[0,1,0]
	s_waitcnt lgkmcnt(4)
	s_cmp_eq_u32 s14, 0
	s_cbranch_scc1 .Lrw_skip_d0
	v_add_f32_dpp v48, v48, v48 row_ror:8 row_mask:0xf bank_mask:0x3
	v_add_f32_dpp v49, v49, v49 row_ror:8 row_mask:0xf bank_mask:0x3
	v_add_f32_dpp v50, v50, v50 row_ror:8 row_mask:0xf bank_mask:0x3
	v_add_f32_dpp v51, v51, v51 row_ror:8 row_mask:0xf bank_mask:0x3
	v_add_f32_dpp v52, v52, v52 row_ror:8 row_mask:0xf bank_mask:0x3
	v_add_f32_dpp v53, v53, v53 row_ror:8 row_mask:0xf bank_mask:0x3
	v_add_f32_dpp v54, v54, v54 row_ror:8 row_mask:0xf bank_mask:0x3
	v_add_f32_dpp v55, v55, v55 row_ror:8 row_mask:0xf bank_mask:0x3
	v_add_f32_dpp v48, v56, v56 row_ror:8 row_mask:0xf bank_mask:0xc
	v_add_f32_dpp v49, v57, v57 row_ror:8 row_mask:0xf bank_mask:0xc
	v_add_f32_dpp v50, v58, v58 row_ror:8 row_mask:0xf bank_mask:0xc
	v_add_f32_dpp v51, v59, v59 row_ror:8 row_mask:0xf bank_mask:0xc
	v_add_f32_dpp v52, v60, v60 row_ror:8 row_mask:0xf bank_mask:0xc
	v_add_f32_dpp v53, v61, v61 row_ror:8 row_mask:0xf bank_mask:0xc
	v_add_f32_dpp v54, v62, v62 row_ror:8 row_mask:0xf bank_mask:0xc
	v_add_f32_dpp v55, v63, v63 row_ror:8 row_mask:0xf bank_mask:0xc
	v_add_f32_dpp v48, v48, v48 row_ror:12 row_mask:0xf bank_mask:0x5
	v_add_f32_dpp v49, v49, v49 row_ror:12 row_mask:0xf bank_mask:0x5
	v_add_f32_dpp v50, v50, v50 row_ror:12 row_mask:0xf bank_mask:0x5
	v_add_f32_dpp v51, v51, v51 row_ror:12 row_mask:0xf bank_mask:0x5
	v_add_f32_dpp v48, v52, v52 row_ror:4 row_mask:0xf bank_mask:0xa
	v_add_f32_dpp v49, v53, v53 row_ror:4 row_mask:0xf bank_mask:0xa
	v_add_f32_dpp v50, v54, v54 row_ror:4 row_mask:0xf bank_mask:0xa
	v_add_f32_dpp v51, v55, v55 row_ror:4 row_mask:0xf bank_mask:0xa
	v_add_f32_dpp v64, v48, v48 quad_perm:[2,3,0,1] row_mask:0xf bank_mask:0xf bound_ctrl:1
	v_add_f32_dpp v65, v50, v50 quad_perm:[2,3,0,1] row_mask:0xf bank_mask:0xf bound_ctrl:1
	v_cndmask_b32_e64 v56, v64, v65, s[50:51]
	v_add_f32_dpp v64, v49, v49 quad_perm:[2,3,0,1] row_mask:0xf bank_mask:0xf bound_ctrl:1
	v_add_f32_dpp v65, v51, v51 quad_perm:[2,3,0,1] row_mask:0xf bank_mask:0xf bound_ctrl:1
	v_cndmask_b32_e64 v57, v64, v65, s[50:51]
	v_add_f32_dpp v64, v56, v56 quad_perm:[1,0,3,2] row_mask:0xf bank_mask:0xf bound_ctrl:1
	s_nop 0
	v_add_f32_dpp v65, v57, v57 quad_perm:[1,0,3,2] row_mask:0xf bank_mask:0xf bound_ctrl:1
	v_cndmask_b32_e64 v66, v64, v65, s[48:49]
	v_cvt_pk_bf16_f32 v66, v66, v66
	global_store_short v8, v66, s[12:13]
	s_add_u32 s12, s12, 0x8000
	s_addc_u32 s13, s13, 0
.Lrw_skip_d0:
	ds_read_b64 v[84:85], v6 offset:3088
	v_fma_mix_f32 v14, v10, v38, 0 op_sel:[0,0,0] op_sel_hi:[0,1,0]
	v_fma_mix_f32 v48, v10, v32, 0 op_sel:[0,0,0] op_sel_hi:[0,1,0]
	v_fma_mix_f32 v14, v11, v38, v14 op_sel:[0,1,0] op_sel_hi:[0,1,0]
	ds_read_b128 v[86:89], v6 offset:3344
	v_fma_mix_f32 v48, v11, v32, v48 op_sel:[0,1,0] op_sel_hi:[0,1,0]
	v_fma_mix_f32 v14, v12, v39, v14 op_sel:[0,0,0] op_sel_hi:[0,1,0]
	v_fma_mix_f32 v48, v12, v33, v48 op_sel:[0,0,0] op_sel_hi:[0,1,0]
	ds_read_b128 v[90:93], v6 offset:3600
	v_fma_mix_f32 v14, v13, v39, v14 op_sel:[0,1,0] op_sel_hi:[0,1,0]
	v_fma_mix_f32 v16, v10, v36, 0 op_sel:[0,0,0] op_sel_hi:[0,1,0]
	v_fma_mix_f32 v17, v11, v36, 0 op_sel:[0,1,0] op_sel_hi:[0,1,0]
	ds_read_u16 v94, v7 offset:3088
	v_add_f32_dpp v20, v14, v14 quad_perm:[1,0,3,2] row_mask:0xf bank_mask:0xf bound_ctrl:1
	v_fma_mix_f32 v48, v13, v33, v48 op_sel:[0,1,0] op_sel_hi:[0,1,0]
	v_fma_mix_f32 v18, v12, v37, 0 op_sel:[0,0,0] op_sel_hi:[0,1,0]
	v_add_f32_dpp v20, v20, v20 quad_perm:[2,3,0,1] row_mask:0xf bank_mask:0xf bound_ctrl:1
	v_fma_mix_f32 v19, v13, v37, 0 op_sel:[0,1,0] op_sel_hi:[0,1,0]
	v_fma_mix_f32 v16, v46, v42, v16 op_sel:[0,0,0] op_sel_hi:[1,1,0]
	v_add_f32_dpp v20, v20, v20 row_half_mirror row_mask:0xf bank_mask:0xf bound_ctrl:1
	v_fma_mix_f32 v17, v46, v42, v17 op_sel:[0,1,0] op_sel_hi:[1,1,0]
	v_fma_mix_f32 v18, v46, v43, v18 op_sel:[0,0,0] op_sel_hi:[1,1,0]
	v_add_f32_dpp v20, v20, v20 row_mirror row_mask:0xf bank_mask:0xf bound_ctrl:1
	v_fma_mix_f32 v19, v46, v43, v19 op_sel:[0,1,0] op_sel_hi:[1,1,0]
	v_fma_mix_f32 v10, v20, v40, v16 op_sel:[0,0,0] op_sel_hi:[0,1,0]
	v_fma_mix_f32 v11, v20, v40, v17 op_sel:[0,1,0] op_sel_hi:[0,1,0]
	v_fma_mix_f32 v12, v20, v41, v18 op_sel:[0,0,0] op_sel_hi:[0,1,0]
	v_fma_mix_f32 v13, v20, v41, v19 op_sel:[0,1,0] op_sel_hi:[0,1,0]
	s_waitcnt lgkmcnt(4)
	ds_read_b64 v[24:25], v6 offset:4112
	v_fma_mix_f32 v14, v10, v74, 0 op_sel:[0,0,0] op_sel_hi:[0,1,0]
	v_fma_mix_f32 v49, v10, v44, 0 op_sel:[0,0,0] op_sel_hi:[0,1,0]
	v_fma_mix_f32 v14, v11, v74, v14 op_sel:[0,1,0] op_sel_hi:[0,1,0]
	ds_read_b128 v[26:29], v6 offset:4368
	v_fma_mix_f32 v49, v11, v44, v49 op_sel:[0,1,0] op_sel_hi:[0,1,0]
	v_fma_mix_f32 v14, v12, v75, v14 op_sel:[0,0,0] op_sel_hi:[0,1,0]
	v_fma_mix_f32 v49, v12, v45, v49 op_sel:[0,0,0] op_sel_hi:[0,1,0]
	ds_read_b128 v[30:33], v6 offset:4624
	v_fma_mix_f32 v14, v13, v75, v14 op_sel:[0,1,0] op_sel_hi:[0,1,0]
	v_fma_mix_f32 v16, v10, v72, 0 op_sel:[0,0,0] op_sel_hi:[0,1,0]
	v_fma_mix_f32 v17, v11, v72, 0 op_sel:[0,1,0] op_sel_hi:[0,1,0]
	ds_read_u16 v34, v7 offset:4112
	v_add_f32_dpp v20, v14, v14 quad_perm:[1,0,3,2] row_mask:0xf bank_mask:0xf bound_ctrl:1
	v_fma_mix_f32 v49, v13, v45, v49 op_sel:[0,1,0] op_sel_hi:[0,1,0]
	v_fma_mix_f32 v18, v12, v73, 0 op_sel:[0,0,0] op_sel_hi:[0,1,0]
	v_add_f32_dpp v20, v20, v20 quad_perm:[2,3,0,1] row_mask:0xf bank_mask:0xf bound_ctrl:1
	v_fma_mix_f32 v19, v13, v73, 0 op_sel:[0,1,0] op_sel_hi:[0,1,0]
	v_fma_mix_f32 v16, v82, v78, v16 op_sel:[0,0,0] op_sel_hi:[1,1,0]
	v_add_f32_dpp v20, v20, v20 row_half_mirror row_mask:0xf bank_mask:0xf bound_ctrl:1
	v_fma_mix_f32 v17, v82, v78, v17 op_sel:[0,1,0] op_sel_hi:[1,1,0]
	v_fma_mix_f32 v18, v82, v79, v18 op_sel:[0,0,0] op_sel_hi:[1,1,0]
	v_add_f32_dpp v20, v20, v20 row_mirror row_mask:0xf bank_mask:0xf bound_ctrl:1
	v_fma_mix_f32 v19, v82, v79, v19 op_sel:[0,1,0] op_sel_hi:[1,1,0]
	v_fma_mix_f32 v10, v20, v76, v16 op_sel:[0,0,0] op_sel_hi:[0,1,0]
	v_fma_mix_f32 v11, v20, v76, v17 op_sel:[0,1,0] op_sel_hi:[0,1,0]
	v_fma_mix_f32 v12, v20, v77, v18 op_sel:[0,0,0] op_sel_hi:[0,1,0]
	v_fma_mix_f32 v13, v20, v77, v19 op_sel:[0,1,0] op_sel_hi:[0,1,0]
	s_waitcnt lgkmcnt(4)
	ds_read_b64 v[36:37], v6 offset:5136
	v_fma_mix_f32 v14, v10, v86, 0 op_sel:[0,0,0] op_sel_hi:[0,1,0]
	v_fma_mix_f32 v50, v10, v80, 0 op_sel:[0,0,0] op_sel_hi:[0,1,0]
	v_fma_mix_f32 v14, v11, v86, v14 op_sel:[0,1,0] op_sel_hi:[0,1,0]
	ds_read_b128 v[38:41], v6 offset:5392
	v_fma_mix_f32 v50, v11, v80, v50 op_sel:[0,1,0] op_sel_hi:[0,1,0]
	v_fma_mix_f32 v14, v12, v87, v14 op_sel:[0,0,0] op_sel_hi:[0,1,0]
	v_fma_mix_f32 v50, v12, v81, v50 op_sel:[0,0,0] op_sel_hi:[0,1,0]
	ds_read_b128 v[42:45], v6 offset:5648
	v_fma_mix_f32 v14, v13, v87, v14 op_sel:[0,1,0] op_sel_hi:[0,1,0]
	v_fma_mix_f32 v16, v10, v84, 0 op_sel:[0,0,0] op_sel_hi:[0,1,0]
	v_fma_mix_f32 v17, v11, v84, 0 op_sel:[0,1,0] op_sel_hi:[0,1,0]
	ds_read_u16 v46, v7 offset:5136
	v_add_f32_dpp v20, v14, v14 quad_perm:[1,0,3,2] row_mask:0xf bank_mask:0xf bound_ctrl:1
	v_fma_mix_f32 v50, v13, v81, v50 op_sel:[0,1,0] op_sel_hi:[0,1,0]
	v_fma_mix_f32 v18, v12, v85, 0 op_sel:[0,0,0] op_sel_hi:[0,1,0]
	v_add_f32_dpp v20, v20, v20 quad_perm:[2,3,0,1] row_mask:0xf bank_mask:0xf bound_ctrl:1
	v_fma_mix_f32 v19, v13, v85, 0 op_sel:[0,1,0] op_sel_hi:[0,1,0]
	v_fma_mix_f32 v16, v94, v90, v16 op_sel:[0,0,0] op_sel_hi:[1,1,0]
	v_add_f32_dpp v20, v20, v20 row_half_mirror row_mask:0xf bank_mask:0xf bound_ctrl:1
	v_fma_mix_f32 v17, v94, v90, v17 op_sel:[0,1,0] op_sel_hi:[1,1,0]
	v_fma_mix_f32 v18, v94, v91, v18 op_sel:[0,0,0] op_sel_hi:[1,1,0]
	v_add_f32_dpp v20, v20, v20 row_mirror row_mask:0xf bank_mask:0xf bound_ctrl:1
	v_fma_mix_f32 v19, v94, v91, v19 op_sel:[0,1,0] op_sel_hi:[1,1,0]
	v_fma_mix_f32 v10, v20, v88, v16 op_sel:[0,0,0] op_sel_hi:[0,1,0]
	v_fma_mix_f32 v11, v20, v88, v17 op_sel:[0,1,0] op_sel_hi:[0,1,0]
	v_fma_mix_f32 v12, v20, v89, v18 op_sel:[0,0,0] op_sel_hi:[0,1,0]
	v_fma_mix_f32 v13, v20, v89, v19 op_sel:[0,1,0] op_sel_hi:[0,1,0]
	s_waitcnt lgkmcnt(4)
	ds_read_b64 v[72:73], v6 offset:6160
	v_fma_mix_f32 v14, v10, v26, 0 op_sel:[0,0,0] op_sel_hi:[0,1,0]
	v_fma_mix_f32 v51, v10, v92, 0 op_sel:[0,0,0] op_sel_hi:[0,1,0]
	v_fma_mix_f32 v14, v11, v26, v14 op_sel:[0,1,0] op_sel_hi:[0,1,0]
	ds_read_b128 v[74:77], v6 offset:6416
	v_fma_mix_f32 v51, v11, v92, v51 op_sel:[0,1,0] op_sel_hi:[0,1,0]
	v_fma_mix_f32 v14, v12, v27, v14 op_sel:[0,0,0] op_sel_hi:[0,1,0]
	v_fma_mix_f32 v51, v12, v93, v51 op_sel:[0,0,0] op_sel_hi:[0,1,0]
	ds_read_b128 v[78:81], v6 offset:6672
	v_fma_mix_f32 v14, v13, v27, v14 op_sel:[0,1,0] op_sel_hi:[0,1,0]
	v_fma_mix_f32 v16, v10, v24, 0 op_sel:[0,0,0] op_sel_hi:[0,1,0]
	v_fma_mix_f32 v17, v11, v24, 0 op_sel:[0,1,0] op_sel_hi:[0,1,0]
	ds_read_u16 v82, v7 offset:6160
	v_add_f32_dpp v20, v14, v14 quad_perm:[1,0,3,2] row_mask:0xf bank_mask:0xf bound_ctrl:1
	v_fma_mix_f32 v51, v13, v93, v51 op_sel:[0,1,0] op_sel_hi:[0,1,0]
	v_fma_mix_f32 v18, v12, v25, 0 op_sel:[0,0,0] op_sel_hi:[0,1,0]
	v_add_f32_dpp v20, v20, v20 quad_perm:[2,3,0,1] row_mask:0xf bank_mask:0xf bound_ctrl:1
	v_fma_mix_f32 v19, v13, v25, 0 op_sel:[0,1,0] op_sel_hi:[0,1,0]
	v_fma_mix_f32 v16, v34, v30, v16 op_sel:[0,0,0] op_sel_hi:[1,1,0]
	v_add_f32_dpp v20, v20, v20 row_half_mirror row_mask:0xf bank_mask:0xf bound_ctrl:1
	v_fma_mix_f32 v17, v34, v30, v17 op_sel:[0,1,0] op_sel_hi:[1,1,0]
	v_fma_mix_f32 v18, v34, v31, v18 op_sel:[0,0,0] op_sel_hi:[1,1,0]
	v_add_f32_dpp v20, v20, v20 row_mirror row_mask:0xf bank_mask:0xf bound_ctrl:1
	v_fma_mix_f32 v19, v34, v31, v19 op_sel:[0,1,0] op_sel_hi:[1,1,0]
	v_fma_mix_f32 v10, v20, v28, v16 op_sel:[0,0,0] op_sel_hi:[0,1,0]
	v_fma_mix_f32 v11, v20, v28, v17 op_sel:[0,1,0] op_sel_hi:[0,1,0]
	v_fma_mix_f32 v12, v20, v29, v18 op_sel:[0,0,0] op_sel_hi:[0,1,0]
	v_fma_mix_f32 v13, v20, v29, v19 op_sel:[0,1,0] op_sel_hi:[0,1,0]
	s_waitcnt lgkmcnt(4)
	ds_read_b64 v[84:85], v6 offset:7184
	v_fma_mix_f32 v14, v10, v38, 0 op_sel:[0,0,0] op_sel_hi:[0,1,0]
	v_fma_mix_f32 v52, v10, v32, 0 op_sel:[0,0,0] op_sel_hi:[0,1,0]
	v_fma_mix_f32 v14, v11, v38, v14 op_sel:[0,1,0] op_sel_hi:[0,1,0]
	ds_read_b128 v[86:89], v6 offset:7440
	v_fma_mix_f32 v52, v11, v32, v52 op_sel:[0,1,0] op_sel_hi:[0,1,0]
	v_fma_mix_f32 v14, v12, v39, v14 op_sel:[0,0,0] op_sel_hi:[0,1,0]
	v_fma_mix_f32 v52, v12, v33, v52 op_sel:[0,0,0] op_sel_hi:[0,1,0]
	ds_read_b128 v[90:93], v6 offset:7696
	v_fma_mix_f32 v14, v13, v39, v14 op_sel:[0,1,0] op_sel_hi:[0,1,0]
	v_fma_mix_f32 v16, v10, v36, 0 op_sel:[0,0,0] op_sel_hi:[0,1,0]
	v_fma_mix_f32 v17, v11, v36, 0 op_sel:[0,1,0] op_sel_hi:[0,1,0]
	ds_read_u16 v94, v7 offset:7184
	v_add_f32_dpp v20, v14, v14 quad_perm:[1,0,3,2] row_mask:0xf bank_mask:0xf bound_ctrl:1
	v_fma_mix_f32 v52, v13, v33, v52 op_sel:[0,1,0] op_sel_hi:[0,1,0]
	v_fma_mix_f32 v18, v12, v37, 0 op_sel:[0,0,0] op_sel_hi:[0,1,0]
	v_add_f32_dpp v20, v20, v20 quad_perm:[2,3,0,1] row_mask:0xf bank_mask:0xf bound_ctrl:1
	v_fma_mix_f32 v19, v13, v37, 0 op_sel:[0,1,0] op_sel_hi:[0,1,0]
	v_fma_mix_f32 v16, v46, v42, v16 op_sel:[0,0,0] op_sel_hi:[1,1,0]
	v_add_f32_dpp v20, v20, v20 row_half_mirror row_mask:0xf bank_mask:0xf bound_ctrl:1
	v_fma_mix_f32 v17, v46, v42, v17 op_sel:[0,1,0] op_sel_hi:[1,1,0]
	v_fma_mix_f32 v18, v46, v43, v18 op_sel:[0,0,0] op_sel_hi:[1,1,0]
	v_add_f32_dpp v20, v20, v20 row_mirror row_mask:0xf bank_mask:0xf bound_ctrl:1
	v_fma_mix_f32 v19, v46, v43, v19 op_sel:[0,1,0] op_sel_hi:[1,1,0]
	v_fma_mix_f32 v10, v20, v40, v16 op_sel:[0,0,0] op_sel_hi:[0,1,0]
	v_fma_mix_f32 v11, v20, v40, v17 op_sel:[0,1,0] op_sel_hi:[0,1,0]
	v_fma_mix_f32 v12, v20, v41, v18 op_sel:[0,0,0] op_sel_hi:[0,1,0]
	v_fma_mix_f32 v13, v20, v41, v19 op_sel:[0,1,0] op_sel_hi:[0,1,0]
	s_waitcnt lgkmcnt(4)
	ds_read_b64 v[24:25], v6 offset:8208
	v_fma_mix_f32 v14, v10, v74, 0 op_sel:[0,0,0] op_sel_hi:[0,1,0]
	v_fma_mix_f32 v53, v10, v44, 0 op_sel:[0,0,0] op_sel_hi:[0,1,0]
	v_fma_mix_f32 v14, v11, v74, v14 op_sel:[0,1,0] op_sel_hi:[0,1,0]
	ds_read_b128 v[26:29], v6 offset:8464
	v_fma_mix_f32 v53, v11, v44, v53 op_sel:[0,1,0] op_sel_hi:[0,1,0]
	v_fma_mix_f32 v14, v12, v75, v14 op_sel:[0,0,0] op_sel_hi:[0,1,0]
	v_fma_mix_f32 v53, v12, v45, v53 op_sel:[0,0,0] op_sel_hi:[0,1,0]
	ds_read_b128 v[30:33], v6 offset:8720
	v_fma_mix_f32 v14, v13, v75, v14 op_sel:[0,1,0] op_sel_hi:[0,1,0]
	v_fma_mix_f32 v16, v10, v72, 0 op_sel:[0,0,0] op_sel_hi:[0,1,0]
	v_fma_mix_f32 v17, v11, v72, 0 op_sel:[0,1,0] op_sel_hi:[0,1,0]
	ds_read_u16 v34, v7 offset:8208
	v_add_f32_dpp v20, v14, v14 quad_perm:[1,0,3,2] row_mask:0xf bank_mask:0xf bound_ctrl:1
	v_fma_mix_f32 v53, v13, v45, v53 op_sel:[0,1,0] op_sel_hi:[0,1,0]
	v_fma_mix_f32 v18, v12, v73, 0 op_sel:[0,0,0] op_sel_hi:[0,1,0]
	v_add_f32_dpp v20, v20, v20 quad_perm:[2,3,0,1] row_mask:0xf bank_mask:0xf bound_ctrl:1
	v_fma_mix_f32 v19, v13, v73, 0 op_sel:[0,1,0] op_sel_hi:[0,1,0]
	v_fma_mix_f32 v16, v82, v78, v16 op_sel:[0,0,0] op_sel_hi:[1,1,0]
	v_add_f32_dpp v20, v20, v20 row_half_mirror row_mask:0xf bank_mask:0xf bound_ctrl:1
	v_fma_mix_f32 v17, v82, v78, v17 op_sel:[0,1,0] op_sel_hi:[1,1,0]
	v_fma_mix_f32 v18, v82, v79, v18 op_sel:[0,0,0] op_sel_hi:[1,1,0]
	v_add_f32_dpp v20, v20, v20 row_mirror row_mask:0xf bank_mask:0xf bound_ctrl:1
	v_fma_mix_f32 v19, v82, v79, v19 op_sel:[0,1,0] op_sel_hi:[1,1,0]
	v_fma_mix_f32 v10, v20, v76, v16 op_sel:[0,0,0] op_sel_hi:[0,1,0]
	v_fma_mix_f32 v11, v20, v76, v17 op_sel:[0,1,0] op_sel_hi:[0,1,0]
	v_fma_mix_f32 v12, v20, v77, v18 op_sel:[0,0,0] op_sel_hi:[0,1,0]
	v_fma_mix_f32 v13, v20, v77, v19 op_sel:[0,1,0] op_sel_hi:[0,1,0]
	s_waitcnt lgkmcnt(4)
	ds_read_b64 v[36:37], v6 offset:9232
	v_fma_mix_f32 v14, v10, v86, 0 op_sel:[0,0,0] op_sel_hi:[0,1,0]
	v_fma_mix_f32 v54, v10, v80, 0 op_sel:[0,0,0] op_sel_hi:[0,1,0]
	v_fma_mix_f32 v14, v11, v86, v14 op_sel:[0,1,0] op_sel_hi:[0,1,0]
	ds_read_b128 v[38:41], v6 offset:9488
	v_fma_mix_f32 v54, v11, v80, v54 op_sel:[0,1,0] op_sel_hi:[0,1,0]
	v_fma_mix_f32 v14, v12, v87, v14 op_sel:[0,0,0] op_sel_hi:[0,1,0]
	v_fma_mix_f32 v54, v12, v81, v54 op_sel:[0,0,0] op_sel_hi:[0,1,0]
	ds_read_b128 v[42:45], v6 offset:9744
	v_fma_mix_f32 v14, v13, v87, v14 op_sel:[0,1,0] op_sel_hi:[0,1,0]
	v_fma_mix_f32 v16, v10, v84, 0 op_sel:[0,0,0] op_sel_hi:[0,1,0]
	v_fma_mix_f32 v17, v11, v84, 0 op_sel:[0,1,0] op_sel_hi:[0,1,0]
	ds_read_u16 v46, v7 offset:9232
	v_add_f32_dpp v20, v14, v14 quad_perm:[1,0,3,2] row_mask:0xf bank_mask:0xf bound_ctrl:1
	v_fma_mix_f32 v54, v13, v81, v54 op_sel:[0,1,0] op_sel_hi:[0,1,0]
	v_fma_mix_f32 v18, v12, v85, 0 op_sel:[0,0,0] op_sel_hi:[0,1,0]
	v_add_f32_dpp v20, v20, v20 quad_perm:[2,3,0,1] row_mask:0xf bank_mask:0xf bound_ctrl:1
	v_fma_mix_f32 v19, v13, v85, 0 op_sel:[0,1,0] op_sel_hi:[0,1,0]
	v_fma_mix_f32 v16, v94, v90, v16 op_sel:[0,0,0] op_sel_hi:[1,1,0]
	v_add_f32_dpp v20, v20, v20 row_half_mirror row_mask:0xf bank_mask:0xf bound_ctrl:1
	v_fma_mix_f32 v17, v94, v90, v17 op_sel:[0,1,0] op_sel_hi:[1,1,0]
	v_fma_mix_f32 v18, v94, v91, v18 op_sel:[0,0,0] op_sel_hi:[1,1,0]
	v_add_f32_dpp v20, v20, v20 row_mirror row_mask:0xf bank_mask:0xf bound_ctrl:1
	v_fma_mix_f32 v19, v94, v91, v19 op_sel:[0,1,0] op_sel_hi:[1,1,0]
	v_fma_mix_f32 v10, v20, v88, v16 op_sel:[0,0,0] op_sel_hi:[0,1,0]
	v_fma_mix_f32 v11, v20, v88, v17 op_sel:[0,1,0] op_sel_hi:[0,1,0]
	v_fma_mix_f32 v12, v20, v89, v18 op_sel:[0,0,0] op_sel_hi:[0,1,0]
	v_fma_mix_f32 v13, v20, v89, v19 op_sel:[0,1,0] op_sel_hi:[0,1,0]
	s_waitcnt lgkmcnt(4)
	ds_read_b64 v[72:73], v6 offset:10256
	v_fma_mix_f32 v14, v10, v26, 0 op_sel:[0,0,0] op_sel_hi:[0,1,0]
	v_fma_mix_f32 v55, v10, v92, 0 op_sel:[0,0,0] op_sel_hi:[0,1,0]
	v_fma_mix_f32 v14, v11, v26, v14 op_sel:[0,1,0] op_sel_hi:[0,1,0]
	ds_read_b128 v[74:77], v6 offset:10512
	v_fma_mix_f32 v55, v11, v92, v55 op_sel:[0,1,0] op_sel_hi:[0,1,0]
	v_fma_mix_f32 v14, v12, v27, v14 op_sel:[0,0,0] op_sel_hi:[0,1,0]
	v_fma_mix_f32 v55, v12, v93, v55 op_sel:[0,0,0] op_sel_hi:[0,1,0]
	ds_read_b128 v[78:81], v6 offset:10768
	v_fma_mix_f32 v14, v13, v27, v14 op_sel:[0,1,0] op_sel_hi:[0,1,0]
	v_fma_mix_f32 v16, v10, v24, 0 op_sel:[0,0,0] op_sel_hi:[0,1,0]
	v_fma_mix_f32 v17, v11, v24, 0 op_sel:[0,1,0] op_sel_hi:[0,1,0]
	ds_read_u16 v82, v7 offset:10256
	v_add_f32_dpp v20, v14, v14 quad_perm:[1,0,3,2] row_mask:0xf bank_mask:0xf bound_ctrl:1
	v_fma_mix_f32 v55, v13, v93, v55 op_sel:[0,1,0] op_sel_hi:[0,1,0]
	v_fma_mix_f32 v18, v12, v25, 0 op_sel:[0,0,0] op_sel_hi:[0,1,0]
	v_add_f32_dpp v20, v20, v20 quad_perm:[2,3,0,1] row_mask:0xf bank_mask:0xf bound_ctrl:1
	v_fma_mix_f32 v19, v13, v25, 0 op_sel:[0,1,0] op_sel_hi:[0,1,0]
	v_fma_mix_f32 v16, v34, v30, v16 op_sel:[0,0,0] op_sel_hi:[1,1,0]
	v_add_f32_dpp v20, v20, v20 row_half_mirror row_mask:0xf bank_mask:0xf bound_ctrl:1
	v_fma_mix_f32 v17, v34, v30, v17 op_sel:[0,1,0] op_sel_hi:[1,1,0]
	v_fma_mix_f32 v18, v34, v31, v18 op_sel:[0,0,0] op_sel_hi:[1,1,0]
	v_add_f32_dpp v20, v20, v20 row_mirror row_mask:0xf bank_mask:0xf bound_ctrl:1
	v_fma_mix_f32 v19, v34, v31, v19 op_sel:[0,1,0] op_sel_hi:[1,1,0]
	v_fma_mix_f32 v10, v20, v28, v16 op_sel:[0,0,0] op_sel_hi:[0,1,0]
	v_fma_mix_f32 v11, v20, v28, v17 op_sel:[0,1,0] op_sel_hi:[0,1,0]
	v_fma_mix_f32 v12, v20, v29, v18 op_sel:[0,0,0] op_sel_hi:[0,1,0]
	v_fma_mix_f32 v13, v20, v29, v19 op_sel:[0,1,0] op_sel_hi:[0,1,0]
	s_waitcnt lgkmcnt(4)
	ds_read_b64 v[84:85], v6 offset:11280
	v_fma_mix_f32 v14, v10, v38, 0 op_sel:[0,0,0] op_sel_hi:[0,1,0]
	v_fma_mix_f32 v56, v10, v32, 0 op_sel:[0,0,0] op_sel_hi:[0,1,0]
	v_fma_mix_f32 v14, v11, v38, v14 op_sel:[0,1,0] op_sel_hi:[0,1,0]
	ds_read_b128 v[86:89], v6 offset:11536
	v_fma_mix_f32 v56, v11, v32, v56 op_sel:[0,1,0] op_sel_hi:[0,1,0]
	v_fma_mix_f32 v14, v12, v39, v14 op_sel:[0,0,0] op_sel_hi:[0,1,0]
	v_fma_mix_f32 v56, v12, v33, v56 op_sel:[0,0,0] op_sel_hi:[0,1,0]
	ds_read_b128 v[90:93], v6 offset:11792
	v_fma_mix_f32 v14, v13, v39, v14 op_sel:[0,1,0] op_sel_hi:[0,1,0]
	v_fma_mix_f32 v16, v10, v36, 0 op_sel:[0,0,0] op_sel_hi:[0,1,0]
	v_fma_mix_f32 v17, v11, v36, 0 op_sel:[0,1,0] op_sel_hi:[0,1,0]
	ds_read_u16 v94, v7 offset:11280
	v_add_f32_dpp v20, v14, v14 quad_perm:[1,0,3,2] row_mask:0xf bank_mask:0xf bound_ctrl:1
	v_fma_mix_f32 v56, v13, v33, v56 op_sel:[0,1,0] op_sel_hi:[0,1,0]
	v_fma_mix_f32 v18, v12, v37, 0 op_sel:[0,0,0] op_sel_hi:[0,1,0]
	v_add_f32_dpp v20, v20, v20 quad_perm:[2,3,0,1] row_mask:0xf bank_mask:0xf bound_ctrl:1
	v_fma_mix_f32 v19, v13, v37, 0 op_sel:[0,1,0] op_sel_hi:[0,1,0]
	v_fma_mix_f32 v16, v46, v42, v16 op_sel:[0,0,0] op_sel_hi:[1,1,0]
	v_add_f32_dpp v20, v20, v20 row_half_mirror row_mask:0xf bank_mask:0xf bound_ctrl:1
	v_fma_mix_f32 v17, v46, v42, v17 op_sel:[0,1,0] op_sel_hi:[1,1,0]
	v_fma_mix_f32 v18, v46, v43, v18 op_sel:[0,0,0] op_sel_hi:[1,1,0]
	v_add_f32_dpp v20, v20, v20 row_mirror row_mask:0xf bank_mask:0xf bound_ctrl:1
	v_fma_mix_f32 v19, v46, v43, v19 op_sel:[0,1,0] op_sel_hi:[1,1,0]
	v_fma_mix_f32 v10, v20, v40, v16 op_sel:[0,0,0] op_sel_hi:[0,1,0]
	v_fma_mix_f32 v11, v20, v40, v17 op_sel:[0,1,0] op_sel_hi:[0,1,0]
	v_fma_mix_f32 v12, v20, v41, v18 op_sel:[0,0,0] op_sel_hi:[0,1,0]
	v_fma_mix_f32 v13, v20, v41, v19 op_sel:[0,1,0] op_sel_hi:[0,1,0]
	s_waitcnt lgkmcnt(4)
	ds_read_b64 v[24:25], v6 offset:12304
	v_fma_mix_f32 v14, v10, v74, 0 op_sel:[0,0,0] op_sel_hi:[0,1,0]
	v_fma_mix_f32 v57, v10, v44, 0 op_sel:[0,0,0] op_sel_hi:[0,1,0]
	v_fma_mix_f32 v14, v11, v74, v14 op_sel:[0,1,0] op_sel_hi:[0,1,0]
	ds_read_b128 v[26:29], v6 offset:12560
	v_fma_mix_f32 v57, v11, v44, v57 op_sel:[0,1,0] op_sel_hi:[0,1,0]
	v_fma_mix_f32 v14, v12, v75, v14 op_sel:[0,0,0] op_sel_hi:[0,1,0]
	v_fma_mix_f32 v57, v12, v45, v57 op_sel:[0,0,0] op_sel_hi:[0,1,0]
	ds_read_b128 v[30:33], v6 offset:12816
	v_fma_mix_f32 v14, v13, v75, v14 op_sel:[0,1,0] op_sel_hi:[0,1,0]
	v_fma_mix_f32 v16, v10, v72, 0 op_sel:[0,0,0] op_sel_hi:[0,1,0]
	v_fma_mix_f32 v17, v11, v72, 0 op_sel:[0,1,0] op_sel_hi:[0,1,0]
	ds_read_u16 v34, v7 offset:12304
	v_add_f32_dpp v20, v14, v14 quad_perm:[1,0,3,2] row_mask:0xf bank_mask:0xf bound_ctrl:1
	v_fma_mix_f32 v57, v13, v45, v57 op_sel:[0,1,0] op_sel_hi:[0,1,0]
	v_fma_mix_f32 v18, v12, v73, 0 op_sel:[0,0,0] op_sel_hi:[0,1,0]
	v_add_f32_dpp v20, v20, v20 quad_perm:[2,3,0,1] row_mask:0xf bank_mask:0xf bound_ctrl:1
	v_fma_mix_f32 v19, v13, v73, 0 op_sel:[0,1,0] op_sel_hi:[0,1,0]
	v_fma_mix_f32 v16, v82, v78, v16 op_sel:[0,0,0] op_sel_hi:[1,1,0]
	v_add_f32_dpp v20, v20, v20 row_half_mirror row_mask:0xf bank_mask:0xf bound_ctrl:1
	v_fma_mix_f32 v17, v82, v78, v17 op_sel:[0,1,0] op_sel_hi:[1,1,0]
	v_fma_mix_f32 v18, v82, v79, v18 op_sel:[0,0,0] op_sel_hi:[1,1,0]
	v_add_f32_dpp v20, v20, v20 row_mirror row_mask:0xf bank_mask:0xf bound_ctrl:1
	v_fma_mix_f32 v19, v82, v79, v19 op_sel:[0,1,0] op_sel_hi:[1,1,0]
	v_fma_mix_f32 v10, v20, v76, v16 op_sel:[0,0,0] op_sel_hi:[0,1,0]
	v_fma_mix_f32 v11, v20, v76, v17 op_sel:[0,1,0] op_sel_hi:[0,1,0]
	v_fma_mix_f32 v12, v20, v77, v18 op_sel:[0,0,0] op_sel_hi:[0,1,0]
	v_fma_mix_f32 v13, v20, v77, v19 op_sel:[0,1,0] op_sel_hi:[0,1,0]
	s_waitcnt lgkmcnt(4)
	ds_read_b64 v[36:37], v6 offset:13328
	v_fma_mix_f32 v14, v10, v86, 0 op_sel:[0,0,0] op_sel_hi:[0,1,0]
	v_fma_mix_f32 v58, v10, v80, 0 op_sel:[0,0,0] op_sel_hi:[0,1,0]
	v_fma_mix_f32 v14, v11, v86, v14 op_sel:[0,1,0] op_sel_hi:[0,1,0]
	ds_read_b128 v[38:41], v6 offset:13584
	v_fma_mix_f32 v58, v11, v80, v58 op_sel:[0,1,0] op_sel_hi:[0,1,0]
	v_fma_mix_f32 v14, v12, v87, v14 op_sel:[0,0,0] op_sel_hi:[0,1,0]
	v_fma_mix_f32 v58, v12, v81, v58 op_sel:[0,0,0] op_sel_hi:[0,1,0]
	ds_read_b128 v[42:45], v6 offset:13840
	v_fma_mix_f32 v14, v13, v87, v14 op_sel:[0,1,0] op_sel_hi:[0,1,0]
	v_fma_mix_f32 v16, v10, v84, 0 op_sel:[0,0,0] op_sel_hi:[0,1,0]
	v_fma_mix_f32 v17, v11, v84, 0 op_sel:[0,1,0] op_sel_hi:[0,1,0]
	ds_read_u16 v46, v7 offset:13328
	v_add_f32_dpp v20, v14, v14 quad_perm:[1,0,3,2] row_mask:0xf bank_mask:0xf bound_ctrl:1
	v_fma_mix_f32 v58, v13, v81, v58 op_sel:[0,1,0] op_sel_hi:[0,1,0]
	v_fma_mix_f32 v18, v12, v85, 0 op_sel:[0,0,0] op_sel_hi:[0,1,0]
	v_add_f32_dpp v20, v20, v20 quad_perm:[2,3,0,1] row_mask:0xf bank_mask:0xf bound_ctrl:1
	v_fma_mix_f32 v19, v13, v85, 0 op_sel:[0,1,0] op_sel_hi:[0,1,0]
	v_fma_mix_f32 v16, v94, v90, v16 op_sel:[0,0,0] op_sel_hi:[1,1,0]
	v_add_f32_dpp v20, v20, v20 row_half_mirror row_mask:0xf bank_mask:0xf bound_ctrl:1
	v_fma_mix_f32 v17, v94, v90, v17 op_sel:[0,1,0] op_sel_hi:[1,1,0]
	v_fma_mix_f32 v18, v94, v91, v18 op_sel:[0,0,0] op_sel_hi:[1,1,0]
	v_add_f32_dpp v20, v20, v20 row_mirror row_mask:0xf bank_mask:0xf bound_ctrl:1
	v_fma_mix_f32 v19, v94, v91, v19 op_sel:[0,1,0] op_sel_hi:[1,1,0]
	v_fma_mix_f32 v10, v20, v88, v16 op_sel:[0,0,0] op_sel_hi:[0,1,0]
	v_fma_mix_f32 v11, v20, v88, v17 op_sel:[0,1,0] op_sel_hi:[0,1,0]
	v_fma_mix_f32 v12, v20, v89, v18 op_sel:[0,0,0] op_sel_hi:[0,1,0]
	v_fma_mix_f32 v13, v20, v89, v19 op_sel:[0,1,0] op_sel_hi:[0,1,0]
	s_waitcnt lgkmcnt(4)
	ds_read_b64 v[72:73], v6 offset:14352
	v_fma_mix_f32 v14, v10, v26, 0 op_sel:[0,0,0] op_sel_hi:[0,1,0]
	v_fma_mix_f32 v59, v10, v92, 0 op_sel:[0,0,0] op_sel_hi:[0,1,0]
	v_fma_mix_f32 v14, v11, v26, v14 op_sel:[0,1,0] op_sel_hi:[0,1,0]
	ds_read_b128 v[74:77], v6 offset:14608
	v_fma_mix_f32 v59, v11, v92, v59 op_sel:[0,1,0] op_sel_hi:[0,1,0]
	v_fma_mix_f32 v14, v12, v27, v14 op_sel:[0,0,0] op_sel_hi:[0,1,0]
	v_fma_mix_f32 v59, v12, v93, v59 op_sel:[0,0,0] op_sel_hi:[0,1,0]
	ds_read_b128 v[78:81], v6 offset:14864
	v_fma_mix_f32 v14, v13, v27, v14 op_sel:[0,1,0] op_sel_hi:[0,1,0]
	v_fma_mix_f32 v16, v10, v24, 0 op_sel:[0,0,0] op_sel_hi:[0,1,0]
	v_fma_mix_f32 v17, v11, v24, 0 op_sel:[0,1,0] op_sel_hi:[0,1,0]
	ds_read_u16 v82, v7 offset:14352
	v_add_f32_dpp v20, v14, v14 quad_perm:[1,0,3,2] row_mask:0xf bank_mask:0xf bound_ctrl:1
	v_fma_mix_f32 v59, v13, v93, v59 op_sel:[0,1,0] op_sel_hi:[0,1,0]
	v_fma_mix_f32 v18, v12, v25, 0 op_sel:[0,0,0] op_sel_hi:[0,1,0]
	v_add_f32_dpp v20, v20, v20 quad_perm:[2,3,0,1] row_mask:0xf bank_mask:0xf bound_ctrl:1
	v_fma_mix_f32 v19, v13, v25, 0 op_sel:[0,1,0] op_sel_hi:[0,1,0]
	v_fma_mix_f32 v16, v34, v30, v16 op_sel:[0,0,0] op_sel_hi:[1,1,0]
	v_add_f32_dpp v20, v20, v20 row_half_mirror row_mask:0xf bank_mask:0xf bound_ctrl:1
	v_fma_mix_f32 v17, v34, v30, v17 op_sel:[0,1,0] op_sel_hi:[1,1,0]
	v_fma_mix_f32 v18, v34, v31, v18 op_sel:[0,0,0] op_sel_hi:[1,1,0]
	v_add_f32_dpp v20, v20, v20 row_mirror row_mask:0xf bank_mask:0xf bound_ctrl:1
	v_fma_mix_f32 v19, v34, v31, v19 op_sel:[0,1,0] op_sel_hi:[1,1,0]
	v_fma_mix_f32 v10, v20, v28, v16 op_sel:[0,0,0] op_sel_hi:[0,1,0]
	v_fma_mix_f32 v11, v20, v28, v17 op_sel:[0,1,0] op_sel_hi:[0,1,0]
	v_fma_mix_f32 v12, v20, v29, v18 op_sel:[0,0,0] op_sel_hi:[0,1,0]
	v_fma_mix_f32 v13, v20, v29, v19 op_sel:[0,1,0] op_sel_hi:[0,1,0]
	s_waitcnt lgkmcnt(4)
; DEVINL u16 f2bf(float a) { return (u16)(pk2(a, 0.f) & 0xffffu); }
; #define RW_STEP2(B) RW_STEP(B, WvA, XA, KrA, vhA, WvB, XB, KrB, vhB); RW_STEP((B) + 1, WvB, XB, KrB, vhB, WvA, XA, KrA, vhA)
; #define RW_STEP4(B) RW_STEP2(B); RW_STEP2((B) + 2)
; template <int DIR>
; DEVINL void rwkv_scan_dir(const Params& p, int task, int lane, int wave) {
;     ...
;   for (int st = 0; st < 4096; st += 32) {
;     RW_STEP(0, WvA, XA, KrA, vhA, WvB, XB, KrB, vhB);
;     if (st > 0) { const int q0 = st - 16 + seg; yo[(long)(DIR ? (4095 - q0) : q0) * 1024] = f2bf(ykeep); }
;     RW_STEP(1, WvB, XB, KrB, vhB, WvA, XA, KrA, vhA);
;     RW_STEP2(2); RW_STEP4(4); RW_STEP4(8); RW_STEP4(12);
;     RW_STEP(16, WvA, XA, KrA, vhA, WvB, XB, KrB, vhB);
;     { const int q0 = st + seg; yo[(long)(DIR ? (4095 - q0) : q0) * 1024] = f2bf(ykeep); }
;     RW_STEP(17, WvB, XB, KrB, vhB, WvA, XA, KrA, vhA);
;     RW_STEP2(18); RW_STEP4(20); RW_STEP4(24); RW_STEP4(28);
;   }
	ds_read_b128 v[100:103], v9
	ds_read_b128 v[104:107], v9 offset:16
	ds_read_b64 v[84:85], v6 offset:15376
	v_fma_mix_f32 v14, v10, v38, 0 op_sel:[0,0,0] op_sel_hi:[0,1,0]
	v_fma_mix_f32 v60, v10, v32, 0 op_sel:[0,0,0] op_sel_hi:[0,1,0]
	v_fma_mix_f32 v14, v11, v38, v14 op_sel:[0,1,0] op_sel_hi:[0,1,0]
	ds_read_b128 v[86:89], v6 offset:15632
	v_fma_mix_f32 v60, v11, v32, v60 op_sel:[0,1,0] op_sel_hi:[0,1,0]
	v_fma_mix_f32 v14, v12, v39, v14 op_sel:[0,0,0] op_sel_hi:[0,1,0]
	v_fma_mix_f32 v60, v12, v33, v60 op_sel:[0,0,0] op_sel_hi:[0,1,0]
	ds_read_b128 v[90:93], v6 offset:15888
	v_fma_mix_f32 v14, v13, v39, v14 op_sel:[0,1,0] op_sel_hi:[0,1,0]
	v_fma_mix_f32 v16, v10, v36, 0 op_sel:[0,0,0] op_sel_hi:[0,1,0]
	v_fma_mix_f32 v17, v11, v36, 0 op_sel:[0,1,0] op_sel_hi:[0,1,0]
	ds_read_u16 v94, v7 offset:15376
	v_add_f32_dpp v20, v14, v14 quad_perm:[1,0,3,2] row_mask:0xf bank_mask:0xf bound_ctrl:1
	v_fma_mix_f32 v60, v13, v33, v60 op_sel:[0,1,0] op_sel_hi:[0,1,0]
	v_fma_mix_f32 v18, v12, v37, 0 op_sel:[0,0,0] op_sel_hi:[0,1,0]
	v_add_f32_dpp v20, v20, v20 quad_perm:[2,3,0,1] row_mask:0xf bank_mask:0xf bound_ctrl:1
	v_fma_mix_f32 v19, v13, v37, 0 op_sel:[0,1,0] op_sel_hi:[0,1,0]
	v_fma_mix_f32 v16, v46, v42, v16 op_sel:[0,0,0] op_sel_hi:[1,1,0]
	v_add_f32_dpp v20, v20, v20 row_half_mirror row_mask:0xf bank_mask:0xf bound_ctrl:1
	v_fma_mix_f32 v17, v46, v42, v17 op_sel:[0,1,0] op_sel_hi:[1,1,0]
	v_fma_mix_f32 v18, v46, v43, v18 op_sel:[0,0,0] op_sel_hi:[1,1,0]
	v_add_f32_dpp v20, v20, v20 row_mirror row_mask:0xf bank_mask:0xf bound_ctrl:1
	v_fma_mix_f32 v19, v46, v43, v19 op_sel:[0,1,0] op_sel_hi:[1,1,0]
	v_fma_mix_f32 v10, v20, v40, v16 op_sel:[0,0,0] op_sel_hi:[0,1,0]
	v_fma_mix_f32 v11, v20, v40, v17 op_sel:[0,1,0] op_sel_hi:[0,1,0]
	v_fma_mix_f32 v12, v20, v41, v18 op_sel:[0,0,0] op_sel_hi:[0,1,0]
	v_fma_mix_f32 v13, v20, v41, v19 op_sel:[0,1,0] op_sel_hi:[0,1,0]
	s_waitcnt lgkmcnt(4)
	v_add_u32_e32 v6, 0x4000, v6
	v_add_u32_e32 v7, 0x4000, v7
	v_and_b32_e32 v6, 0x1ffff, v6
	v_and_b32_e32 v7, 0x1ffff, v7
	ds_read_b64 v[24:25], v6 offset:16
	v_fma_mix_f32 v14, v10, v74, 0 op_sel:[0,0,0] op_sel_hi:[0,1,0]
	v_fma_mix_f32 v61, v10, v44, 0 op_sel:[0,0,0] op_sel_hi:[0,1,0]
	v_fma_mix_f32 v14, v11, v74, v14 op_sel:[0,1,0] op_sel_hi:[0,1,0]
	ds_read_b128 v[26:29], v6 offset:272
	v_fma_mix_f32 v61, v11, v44, v61 op_sel:[0,1,0] op_sel_hi:[0,1,0]
	v_fma_mix_f32 v14, v12, v75, v14 op_sel:[0,0,0] op_sel_hi:[0,1,0]
	v_fma_mix_f32 v61, v12, v45, v61 op_sel:[0,0,0] op_sel_hi:[0,1,0]
	ds_read_b128 v[30:33], v6 offset:528
	v_fma_mix_f32 v14, v13, v75, v14 op_sel:[0,1,0] op_sel_hi:[0,1,0]
	v_fma_mix_f32 v16, v10, v72, 0 op_sel:[0,0,0] op_sel_hi:[0,1,0]
	v_fma_mix_f32 v17, v11, v72, 0 op_sel:[0,1,0] op_sel_hi:[0,1,0]
	ds_read_u16 v34, v7 offset:16
	v_add_f32_dpp v20, v14, v14 quad_perm:[1,0,3,2] row_mask:0xf bank_mask:0xf bound_ctrl:1
	v_fma_mix_f32 v61, v13, v45, v61 op_sel:[0,1,0] op_sel_hi:[0,1,0]
	v_fma_mix_f32 v18, v12, v73, 0 op_sel:[0,0,0] op_sel_hi:[0,1,0]
	v_add_f32_dpp v20, v20, v20 quad_perm:[2,3,0,1] row_mask:0xf bank_mask:0xf bound_ctrl:1
	v_fma_mix_f32 v19, v13, v73, 0 op_sel:[0,1,0] op_sel_hi:[0,1,0]
	v_fma_mix_f32 v16, v82, v78, v16 op_sel:[0,0,0] op_sel_hi:[1,1,0]
	v_add_f32_dpp v20, v20, v20 row_half_mirror row_mask:0xf bank_mask:0xf bound_ctrl:1
	v_fma_mix_f32 v17, v82, v78, v17 op_sel:[0,1,0] op_sel_hi:[1,1,0]
	v_fma_mix_f32 v18, v82, v79, v18 op_sel:[0,0,0] op_sel_hi:[1,1,0]
	v_add_f32_dpp v20, v20, v20 row_mirror row_mask:0xf bank_mask:0xf bound_ctrl:1
	v_fma_mix_f32 v19, v82, v79, v19 op_sel:[0,1,0] op_sel_hi:[1,1,0]
	v_fma_mix_f32 v10, v20, v76, v16 op_sel:[0,0,0] op_sel_hi:[0,1,0]
	v_fma_mix_f32 v11, v20, v76, v17 op_sel:[0,1,0] op_sel_hi:[0,1,0]
	v_fma_mix_f32 v12, v20, v77, v18 op_sel:[0,0,0] op_sel_hi:[0,1,0]
	v_fma_mix_f32 v13, v20, v77, v19 op_sel:[0,1,0] op_sel_hi:[0,1,0]
	s_waitcnt lgkmcnt(4)
	ds_read_b64 v[36:37], v6 offset:1040
	v_fma_mix_f32 v14, v10, v86, 0 op_sel:[0,0,0] op_sel_hi:[0,1,0]
	v_fma_mix_f32 v62, v10, v80, 0 op_sel:[0,0,0] op_sel_hi:[0,1,0]
	v_fma_mix_f32 v14, v11, v86, v14 op_sel:[0,1,0] op_sel_hi:[0,1,0]
	ds_read_b128 v[38:41], v6 offset:1296
	v_fma_mix_f32 v62, v11, v80, v62 op_sel:[0,1,0] op_sel_hi:[0,1,0]
	v_fma_mix_f32 v14, v12, v87, v14 op_sel:[0,0,0] op_sel_hi:[0,1,0]
	v_fma_mix_f32 v62, v12, v81, v62 op_sel:[0,0,0] op_sel_hi:[0,1,0]
	ds_read_b128 v[42:45], v6 offset:1552
	v_fma_mix_f32 v14, v13, v87, v14 op_sel:[0,1,0] op_sel_hi:[0,1,0]
	v_fma_mix_f32 v16, v10, v84, 0 op_sel:[0,0,0] op_sel_hi:[0,1,0]
	v_fma_mix_f32 v17, v11, v84, 0 op_sel:[0,1,0] op_sel_hi:[0,1,0]
	ds_read_u16 v46, v7 offset:1040
	v_add_f32_dpp v20, v14, v14 quad_perm:[1,0,3,2] row_mask:0xf bank_mask:0xf bound_ctrl:1
	v_fma_mix_f32 v62, v13, v81, v62 op_sel:[0,1,0] op_sel_hi:[0,1,0]
	v_fma_mix_f32 v18, v12, v85, 0 op_sel:[0,0,0] op_sel_hi:[0,1,0]
	v_add_f32_dpp v20, v20, v20 quad_perm:[2,3,0,1] row_mask:0xf bank_mask:0xf bound_ctrl:1
	v_fma_mix_f32 v19, v13, v85, 0 op_sel:[0,1,0] op_sel_hi:[0,1,0]
	v_fma_mix_f32 v16, v94, v90, v16 op_sel:[0,0,0] op_sel_hi:[1,1,0]
	v_add_f32_dpp v20, v20, v20 row_half_mirror row_mask:0xf bank_mask:0xf bound_ctrl:1
	v_fma_mix_f32 v17, v94, v90, v17 op_sel:[0,1,0] op_sel_hi:[1,1,0]
	v_fma_mix_f32 v18, v94, v91, v18 op_sel:[0,0,0] op_sel_hi:[1,1,0]
	v_add_f32_dpp v20, v20, v20 row_mirror row_mask:0xf bank_mask:0xf bound_ctrl:1
	v_fma_mix_f32 v19, v94, v91, v19 op_sel:[0,1,0] op_sel_hi:[1,1,0]
	v_fma_mix_f32 v10, v20, v88, v16 op_sel:[0,0,0] op_sel_hi:[0,1,0]
	v_fma_mix_f32 v11, v20, v88, v17 op_sel:[0,1,0] op_sel_hi:[0,1,0]
	v_fma_mix_f32 v12, v20, v89, v18 op_sel:[0,0,0] op_sel_hi:[0,1,0]
	v_fma_mix_f32 v13, v20, v89, v19 op_sel:[0,1,0] op_sel_hi:[0,1,0]
	s_waitcnt lgkmcnt(4)
	s_add_u32 s15, s15, 1
	s_add_u32 s14, s14, 1
	v_mov_b32_e32 v69, s15
	ds_write_b32 v68, v69
	s_cmp_lt_u32 s14, 0x100
	s_cbranch_scc1 .Lrw_blk_d0
; DEVINL u16 f2bf(float a) { return (u16)(pk2(a, 0.f) & 0xffffu); }
; template <int DIR>
; DEVINL void rwkv_scan_dir(const Params& p, int task, int lane, int wave) {
;     ...
;   {
;     const float ylast = allred16(ypart);
;     ykeep = (seg == 15) ? ylast : ykeep;
;     const int q0 = 4096 - 16 + seg; yo[(long)(DIR ? (4095 - q0) : q0) * 1024] = f2bf(ykeep);
;   }
;   asm volatile("s_waitcnt vmcnt(0)" ::: "memory");
	v_fma_mix_f32 v21, v10, v92, 0 op_sel:[0,0,0] op_sel_hi:[0,1,0]
	v_fma_mix_f32 v22, v12, v93, 0 op_sel:[0,0,0] op_sel_hi:[0,1,0]
	v_fma_mix_f32 v21, v11, v92, v21 op_sel:[0,1,0] op_sel_hi:[0,1,0]
	v_fma_mix_f32 v22, v13, v93, v22 op_sel:[0,1,0] op_sel_hi:[0,1,0]
	v_add_f32_e32 v63, v21, v22
	s_nop 1
	v_add_f32_dpp v48, v48, v48 row_ror:8 row_mask:0xf bank_mask:0x3
	v_add_f32_dpp v49, v49, v49 row_ror:8 row_mask:0xf bank_mask:0x3
	v_add_f32_dpp v50, v50, v50 row_ror:8 row_mask:0xf bank_mask:0x3
	v_add_f32_dpp v51, v51, v51 row_ror:8 row_mask:0xf bank_mask:0x3
	v_add_f32_dpp v52, v52, v52 row_ror:8 row_mask:0xf bank_mask:0x3
	v_add_f32_dpp v53, v53, v53 row_ror:8 row_mask:0xf bank_mask:0x3
	v_add_f32_dpp v54, v54, v54 row_ror:8 row_mask:0xf bank_mask:0x3
	v_add_f32_dpp v55, v55, v55 row_ror:8 row_mask:0xf bank_mask:0x3
	v_add_f32_dpp v48, v56, v56 row_ror:8 row_mask:0xf bank_mask:0xc
	v_add_f32_dpp v49, v57, v57 row_ror:8 row_mask:0xf bank_mask:0xc
	v_add_f32_dpp v50, v58, v58 row_ror:8 row_mask:0xf bank_mask:0xc
	v_add_f32_dpp v51, v59, v59 row_ror:8 row_mask:0xf bank_mask:0xc
	v_add_f32_dpp v52, v60, v60 row_ror:8 row_mask:0xf bank_mask:0xc
	v_add_f32_dpp v53, v61, v61 row_ror:8 row_mask:0xf bank_mask:0xc
	v_add_f32_dpp v54, v62, v62 row_ror:8 row_mask:0xf bank_mask:0xc
	v_add_f32_dpp v55, v63, v63 row_ror:8 row_mask:0xf bank_mask:0xc
	v_add_f32_dpp v48, v48, v48 row_ror:12 row_mask:0xf bank_mask:0x5
	v_add_f32_dpp v49, v49, v49 row_ror:12 row_mask:0xf bank_mask:0x5
	v_add_f32_dpp v50, v50, v50 row_ror:12 row_mask:0xf bank_mask:0x5
	v_add_f32_dpp v51, v51, v51 row_ror:12 row_mask:0xf bank_mask:0x5
	v_add_f32_dpp v48, v52, v52 row_ror:4 row_mask:0xf bank_mask:0xa
	v_add_f32_dpp v49, v53, v53 row_ror:4 row_mask:0xf bank_mask:0xa
	v_add_f32_dpp v50, v54, v54 row_ror:4 row_mask:0xf bank_mask:0xa
	v_add_f32_dpp v51, v55, v55 row_ror:4 row_mask:0xf bank_mask:0xa
	v_add_f32_dpp v64, v48, v48 quad_perm:[2,3,0,1] row_mask:0xf bank_mask:0xf bound_ctrl:1
	v_add_f32_dpp v65, v50, v50 quad_perm:[2,3,0,1] row_mask:0xf bank_mask:0xf bound_ctrl:1
	v_cndmask_b32_e64 v56, v64, v65, s[50:51]
	v_add_f32_dpp v64, v49, v49 quad_perm:[2,3,0,1] row_mask:0xf bank_mask:0xf bound_ctrl:1
	v_add_f32_dpp v65, v51, v51 quad_perm:[2,3,0,1] row_mask:0xf bank_mask:0xf bound_ctrl:1
	v_cndmask_b32_e64 v57, v64, v65, s[50:51]
	v_add_f32_dpp v64, v56, v56 quad_perm:[1,0,3,2] row_mask:0xf bank_mask:0xf bound_ctrl:1
	s_nop 0
	v_add_f32_dpp v65, v57, v57 quad_perm:[1,0,3,2] row_mask:0xf bank_mask:0xf bound_ctrl:1
	v_cndmask_b32_e64 v66, v64, v65, s[48:49]
	v_cvt_pk_bf16_f32 v66, v66, v66
	global_store_short v8, v66, s[12:13]
	s_add_u32 s12, s12, 0x8000
	s_addc_u32 s13, s13, 0
	s_branch .Lrw_next

; DEVINL u16 f2bf(float a) { return (u16)(pk2(a, 0.f) & 0xffffu); }
; #define RW_STEP2(B) RW_STEP(B, WvA, XA, KrA, vhA, WvB, XB, KrB, vhB); RW_STEP((B) + 1, WvB, XB, KrB, vhB, WvA, XA, KrA, vhA)
; #define RW_STEP4(B) RW_STEP2(B); RW_STEP2((B) + 2)
; template <int DIR>
; DEVINL void rwkv_scan_dir(const Params& p, int task, int lane, int wave) {
;     ...
;   for (int st = 0; st < 4096; st += 32) {
;     RW_STEP(0, WvA, XA, KrA, vhA, WvB, XB, KrB, vhB);
;     if (st > 0) { const int q0 = st - 16 + seg; yo[(long)(DIR ? (4095 - q0) : q0) * 1024] = f2bf(ykeep); }
;     RW_STEP(1, WvB, XB, KrB, vhB, WvA, XA, KrA, vhA);
;     RW_STEP2(2); RW_STEP4(4); RW_STEP4(8); RW_STEP4(12);
;     RW_STEP(16, WvA, XA, KrA, vhA, WvB, XB, KrB, vhB);
;     { const int q0 = st + seg; yo[(long)(DIR ? (4095 - q0) : q0) * 1024] = f2bf(ykeep); }
.Lrw_ready_d1:
	s_add_u32 s3, s40, s41
	s_and_b32 s3, s3, 0x1ffff
	s_add_u32 s3, s3, 16
	s_mov_b32 m0, s3
	s_nop 0
	global_load_lds_dwordx4 v5, s[10:11] offset:0
	global_load_lds_dwordx4 v5, s[10:11] offset:1024
	global_load_lds_dwordx4 v5, s[10:11] offset:2048
	global_load_lds_dwordx4 v5, s[10:11] offset:3072
	s_sub_u32 s10, s10, 0x4000
	s_subb_u32 s11, s11, 0
	s_sub_u32 s41, s41, 0x4000
	s_and_b32 s41, s41, 0x1ffff
	ds_read_b64 v[72:73], v6 offset:13336
	v_fma_mix_f32 v14, v10, v26, 0 op_sel:[0,0,0] op_sel_hi:[0,1,0]
	v_fma_mix_f32 v63, v10, v92, 0 op_sel:[0,0,0] op_sel_hi:[0,1,0]
	v_fma_mix_f32 v14, v11, v26, v14 op_sel:[0,1,0] op_sel_hi:[0,1,0]
	ds_read_b128 v[74:77], v6 offset:13584
	v_fma_mix_f32 v63, v11, v92, v63 op_sel:[0,1,0] op_sel_hi:[0,1,0]
	v_fma_mix_f32 v14, v12, v27, v14 op_sel:[0,0,0] op_sel_hi:[0,1,0]
	v_fma_mix_f32 v63, v12, v93, v63 op_sel:[0,0,0] op_sel_hi:[0,1,0]
	ds_read_b128 v[78:81], v6 offset:13840
	v_fma_mix_f32 v14, v13, v27, v14 op_sel:[0,1,0] op_sel_hi:[0,1,0]
	v_fma_mix_f32 v16, v10, v24, 0 op_sel:[0,0,0] op_sel_hi:[0,1,0]
	v_fma_mix_f32 v17, v11, v24, 0 op_sel:[0,1,0] op_sel_hi:[0,1,0]
	ds_read_u16 v82, v7 offset:13328
	v_add_f32_dpp v20, v14, v14 quad_perm:[1,0,3,2] row_mask:0xf bank_mask:0xf bound_ctrl:1
	v_fma_mix_f32 v63, v13, v93, v63 op_sel:[0,1,0] op_sel_hi:[0,1,0]
	v_fma_mix_f32 v18, v12, v25, 0 op_sel:[0,0,0] op_sel_hi:[0,1,0]
	v_add_f32_dpp v20, v20, v20 quad_perm:[2,3,0,1] row_mask:0xf bank_mask:0xf bound_ctrl:1
	v_fma_mix_f32 v19, v13, v25, 0 op_sel:[0,1,0] op_sel_hi:[0,1,0]
	v_fma_mix_f32 v16, v34, v30, v16 op_sel:[0,0,0] op_sel_hi:[1,1,0]
	v_add_f32_dpp v20, v20, v20 row_half_mirror row_mask:0xf bank_mask:0xf bound_ctrl:1
	v_fma_mix_f32 v17, v34, v30, v17 op_sel:[0,1,0] op_sel_hi:[1,1,0]
	v_fma_mix_f32 v18, v34, v31, v18 op_sel:[0,0,0] op_sel_hi:[1,1,0]
	v_add_f32_dpp v20, v20, v20 row_mirror row_mask:0xf bank_mask:0xf bound_ctrl:1
	v_fma_mix_f32 v19, v34, v31, v19 op_sel:[0,1,0] op_sel_hi:[1,1,0]
	v_fma_mix_f32 v10, v20, v28, v16 op_sel:[0,0,0] op_sel_hi:[0,1,0]
	v_fma_mix_f32 v11, v20, v28, v17 op_sel:[0,1,0] op_sel_hi:[0,1,0]
	v_fma_mix_f32 v12, v20, v29, v18 op_sel:[0,0,0] op_sel_hi:[0,1,0]
	v_fma_mix_f32 v13, v20, v29, v19 op_sel:[0,1,0] op_sel_hi:[0,1,0]
	s_waitcnt lgkmcnt(4)
	s_cmp_eq_u32 s14, 0
	s_cbranch_scc1 .Lrw_skip_d1
	v_add_f32_dpp v48, v48, v48 row_ror:8 row_mask:0xf bank_mask:0x3
	v_add_f32_dpp v49, v49, v49 row_ror:8 row_mask:0xf bank_mask:0x3
	v_add_f32_dpp v50, v50, v50 row_ror:8 row_mask:0xf bank_mask:0x3
	v_add_f32_dpp v51, v51, v51 row_ror:8 row_mask:0xf bank_mask:0x3
	v_add_f32_dpp v52, v52, v52 row_ror:8 row_mask:0xf bank_mask:0x3
	v_add_f32_dpp v53, v53, v53 row_ror:8 row_mask:0xf bank_mask:0x3
	v_add_f32_dpp v54, v54, v54 row_ror:8 row_mask:0xf bank_mask:0x3
	v_add_f32_dpp v55, v55, v55 row_ror:8 row_mask:0xf bank_mask:0x3
	v_add_f32_dpp v48, v56, v56 row_ror:8 row_mask:0xf bank_mask:0xc
	v_add_f32_dpp v49, v57, v57 row_ror:8 row_mask:0xf bank_mask:0xc
	v_add_f32_dpp v50, v58, v58 row_ror:8 row_mask:0xf bank_mask:0xc
	v_add_f32_dpp v51, v59, v59 row_ror:8 row_mask:0xf bank_mask:0xc
	v_add_f32_dpp v52, v60, v60 row_ror:8 row_mask:0xf bank_mask:0xc
	v_add_f32_dpp v53, v61, v61 row_ror:8 row_mask:0xf bank_mask:0xc
	v_add_f32_dpp v54, v62, v62 row_ror:8 row_mask:0xf bank_mask:0xc
	v_add_f32_dpp v55, v63, v63 row_ror:8 row_mask:0xf bank_mask:0xc
	v_add_f32_dpp v48, v48, v48 row_ror:12 row_mask:0xf bank_mask:0x5
	v_add_f32_dpp v49, v49, v49 row_ror:12 row_mask:0xf bank_mask:0x5
	v_add_f32_dpp v50, v50, v50 row_ror:12 row_mask:0xf bank_mask:0x5
	v_add_f32_dpp v51, v51, v51 row_ror:12 row_mask:0xf bank_mask:0x5
	v_add_f32_dpp v48, v52, v52 row_ror:4 row_mask:0xf bank_mask:0xa
	v_add_f32_dpp v49, v53, v53 row_ror:4 row_mask:0xf bank_mask:0xa
	v_add_f32_dpp v50, v54, v54 row_ror:4 row_mask:0xf bank_mask:0xa
	v_add_f32_dpp v51, v55, v55 row_ror:4 row_mask:0xf bank_mask:0xa
	v_add_f32_dpp v64, v48, v48 quad_perm:[2,3,0,1] row_mask:0xf bank_mask:0xf bound_ctrl:1
	v_add_f32_dpp v65, v50, v50 quad_perm:[2,3,0,1] row_mask:0xf bank_mask:0xf bound_ctrl:1
	v_cndmask_b32_e64 v56, v64, v65, s[50:51]
	v_add_f32_dpp v64, v49, v49 quad_perm:[2,3,0,1] row_mask:0xf bank_mask:0xf bound_ctrl:1
	v_add_f32_dpp v65, v51, v51 quad_perm:[2,3,0,1] row_mask:0xf bank_mask:0xf bound_ctrl:1
	v_cndmask_b32_e64 v57, v64, v65, s[50:51]
	v_add_f32_dpp v64, v56, v56 quad_perm:[1,0,3,2] row_mask:0xf bank_mask:0xf bound_ctrl:1
	s_nop 0
	v_add_f32_dpp v65, v57, v57 quad_perm:[1,0,3,2] row_mask:0xf bank_mask:0xf bound_ctrl:1
	v_cndmask_b32_e64 v66, v64, v65, s[48:49]
	v_cvt_pk_bf16_f32 v66, v66, v66
	global_store_short v8, v66, s[12:13]
	s_sub_u32 s12, s12, 0x8000
	s_subb_u32 s13, s13, 0
.Lrw_skip_d1:
	ds_read_b64 v[84:85], v6 offset:12312
	v_fma_mix_f32 v14, v10, v38, 0 op_sel:[0,0,0] op_sel_hi:[0,1,0]
	v_fma_mix_f32 v48, v10, v32, 0 op_sel:[0,0,0] op_sel_hi:[0,1,0]
	v_fma_mix_f32 v14, v11, v38, v14 op_sel:[0,1,0] op_sel_hi:[0,1,0]
	ds_read_b128 v[86:89], v6 offset:12560
	v_fma_mix_f32 v48, v11, v32, v48 op_sel:[0,1,0] op_sel_hi:[0,1,0]
	v_fma_mix_f32 v14, v12, v39, v14 op_sel:[0,0,0] op_sel_hi:[0,1,0]
	v_fma_mix_f32 v48, v12, v33, v48 op_sel:[0,0,0] op_sel_hi:[0,1,0]
	ds_read_b128 v[90:93], v6 offset:12816
	v_fma_mix_f32 v14, v13, v39, v14 op_sel:[0,1,0] op_sel_hi:[0,1,0]
	v_fma_mix_f32 v16, v10, v36, 0 op_sel:[0,0,0] op_sel_hi:[0,1,0]
	v_fma_mix_f32 v17, v11, v36, 0 op_sel:[0,1,0] op_sel_hi:[0,1,0]
	ds_read_u16 v94, v7 offset:12304
	v_add_f32_dpp v20, v14, v14 quad_perm:[1,0,3,2] row_mask:0xf bank_mask:0xf bound_ctrl:1
	v_fma_mix_f32 v48, v13, v33, v48 op_sel:[0,1,0] op_sel_hi:[0,1,0]
	v_fma_mix_f32 v18, v12, v37, 0 op_sel:[0,0,0] op_sel_hi:[0,1,0]
	v_add_f32_dpp v20, v20, v20 quad_perm:[2,3,0,1] row_mask:0xf bank_mask:0xf bound_ctrl:1
	v_fma_mix_f32 v19, v13, v37, 0 op_sel:[0,1,0] op_sel_hi:[0,1,0]
	v_fma_mix_f32 v16, v46, v42, v16 op_sel:[0,0,0] op_sel_hi:[1,1,0]
	v_add_f32_dpp v20, v20, v20 row_half_mirror row_mask:0xf bank_mask:0xf bound_ctrl:1
	v_fma_mix_f32 v17, v46, v42, v17 op_sel:[0,1,0] op_sel_hi:[1,1,0]
	v_fma_mix_f32 v18, v46, v43, v18 op_sel:[0,0,0] op_sel_hi:[1,1,0]
	v_add_f32_dpp v20, v20, v20 row_mirror row_mask:0xf bank_mask:0xf bound_ctrl:1
	v_fma_mix_f32 v19, v46, v43, v19 op_sel:[0,1,0] op_sel_hi:[1,1,0]
	v_fma_mix_f32 v10, v20, v40, v16 op_sel:[0,0,0] op_sel_hi:[0,1,0]
	v_fma_mix_f32 v11, v20, v40, v17 op_sel:[0,1,0] op_sel_hi:[0,1,0]
	v_fma_mix_f32 v12, v20, v41, v18 op_sel:[0,0,0] op_sel_hi:[0,1,0]
	v_fma_mix_f32 v13, v20, v41, v19 op_sel:[0,1,0] op_sel_hi:[0,1,0]
	s_waitcnt lgkmcnt(4)
	ds_read_b64 v[24:25], v6 offset:11288
	v_fma_mix_f32 v14, v10, v74, 0 op_sel:[0,0,0] op_sel_hi:[0,1,0]
	v_fma_mix_f32 v49, v10, v44, 0 op_sel:[0,0,0] op_sel_hi:[0,1,0]
	v_fma_mix_f32 v14, v11, v74, v14 op_sel:[0,1,0] op_sel_hi:[0,1,0]
	ds_read_b128 v[26:29], v6 offset:11536
	v_fma_mix_f32 v49, v11, v44, v49 op_sel:[0,1,0] op_sel_hi:[0,1,0]
	v_fma_mix_f32 v14, v12, v75, v14 op_sel:[0,0,0] op_sel_hi:[0,1,0]
	v_fma_mix_f32 v49, v12, v45, v49 op_sel:[0,0,0] op_sel_hi:[0,1,0]
	ds_read_b128 v[30:33], v6 offset:11792
	v_fma_mix_f32 v14, v13, v75, v14 op_sel:[0,1,0] op_sel_hi:[0,1,0]
	v_fma_mix_f32 v16, v10, v72, 0 op_sel:[0,0,0] op_sel_hi:[0,1,0]
	v_fma_mix_f32 v17, v11, v72, 0 op_sel:[0,1,0] op_sel_hi:[0,1,0]
	ds_read_u16 v34, v7 offset:11280
	v_add_f32_dpp v20, v14, v14 quad_perm:[1,0,3,2] row_mask:0xf bank_mask:0xf bound_ctrl:1
	v_fma_mix_f32 v49, v13, v45, v49 op_sel:[0,1,0] op_sel_hi:[0,1,0]
	v_fma_mix_f32 v18, v12, v73, 0 op_sel:[0,0,0] op_sel_hi:[0,1,0]
	v_add_f32_dpp v20, v20, v20 quad_perm:[2,3,0,1] row_mask:0xf bank_mask:0xf bound_ctrl:1
	v_fma_mix_f32 v19, v13, v73, 0 op_sel:[0,1,0] op_sel_hi:[0,1,0]
	v_fma_mix_f32 v16, v82, v78, v16 op_sel:[0,0,0] op_sel_hi:[1,1,0]
	v_add_f32_dpp v20, v20, v20 row_half_mirror row_mask:0xf bank_mask:0xf bound_ctrl:1
	v_fma_mix_f32 v17, v82, v78, v17 op_sel:[0,1,0] op_sel_hi:[1,1,0]
	v_fma_mix_f32 v18, v82, v79, v18 op_sel:[0,0,0] op_sel_hi:[1,1,0]
	v_add_f32_dpp v20, v20, v20 row_mirror row_mask:0xf bank_mask:0xf bound_ctrl:1
	v_fma_mix_f32 v19, v82, v79, v19 op_sel:[0,1,0] op_sel_hi:[1,1,0]
	v_fma_mix_f32 v10, v20, v76, v16 op_sel:[0,0,0] op_sel_hi:[0,1,0]
	v_fma_mix_f32 v11, v20, v76, v17 op_sel:[0,1,0] op_sel_hi:[0,1,0]
	v_fma_mix_f32 v12, v20, v77, v18 op_sel:[0,0,0] op_sel_hi:[0,1,0]
	v_fma_mix_f32 v13, v20, v77, v19 op_sel:[0,1,0] op_sel_hi:[0,1,0]
	s_waitcnt lgkmcnt(4)
	ds_read_b64 v[36:37], v6 offset:10264
	v_fma_mix_f32 v14, v10, v86, 0 op_sel:[0,0,0] op_sel_hi:[0,1,0]
	v_fma_mix_f32 v50, v10, v80, 0 op_sel:[0,0,0] op_sel_hi:[0,1,0]
	v_fma_mix_f32 v14, v11, v86, v14 op_sel:[0,1,0] op_sel_hi:[0,1,0]
	ds_read_b128 v[38:41], v6 offset:10512
	v_fma_mix_f32 v50, v11, v80, v50 op_sel:[0,1,0] op_sel_hi:[0,1,0]
	v_fma_mix_f32 v14, v12, v87, v14 op_sel:[0,0,0] op_sel_hi:[0,1,0]
	v_fma_mix_f32 v50, v12, v81, v50 op_sel:[0,0,0] op_sel_hi:[0,1,0]
	ds_read_b128 v[42:45], v6 offset:10768
	v_fma_mix_f32 v14, v13, v87, v14 op_sel:[0,1,0] op_sel_hi:[0,1,0]
	v_fma_mix_f32 v16, v10, v84, 0 op_sel:[0,0,0] op_sel_hi:[0,1,0]
	v_fma_mix_f32 v17, v11, v84, 0 op_sel:[0,1,0] op_sel_hi:[0,1,0]
	ds_read_u16 v46, v7 offset:10256
	v_add_f32_dpp v20, v14, v14 quad_perm:[1,0,3,2] row_mask:0xf bank_mask:0xf bound_ctrl:1
	v_fma_mix_f32 v50, v13, v81, v50 op_sel:[0,1,0] op_sel_hi:[0,1,0]
	v_fma_mix_f32 v18, v12, v85, 0 op_sel:[0,0,0] op_sel_hi:[0,1,0]
	v_add_f32_dpp v20, v20, v20 quad_perm:[2,3,0,1] row_mask:0xf bank_mask:0xf bound_ctrl:1
	v_fma_mix_f32 v19, v13, v85, 0 op_sel:[0,1,0] op_sel_hi:[0,1,0]
	v_fma_mix_f32 v16, v94, v90, v16 op_sel:[0,0,0] op_sel_hi:[1,1,0]
	v_add_f32_dpp v20, v20, v20 row_half_mirror row_mask:0xf bank_mask:0xf bound_ctrl:1
	v_fma_mix_f32 v17, v94, v90, v17 op_sel:[0,1,0] op_sel_hi:[1,1,0]
	v_fma_mix_f32 v18, v94, v91, v18 op_sel:[0,0,0] op_sel_hi:[1,1,0]
	v_add_f32_dpp v20, v20, v20 row_mirror row_mask:0xf bank_mask:0xf bound_ctrl:1
	v_fma_mix_f32 v19, v94, v91, v19 op_sel:[0,1,0] op_sel_hi:[1,1,0]
	v_fma_mix_f32 v10, v20, v88, v16 op_sel:[0,0,0] op_sel_hi:[0,1,0]
	v_fma_mix_f32 v11, v20, v88, v17 op_sel:[0,1,0] op_sel_hi:[0,1,0]
	v_fma_mix_f32 v12, v20, v89, v18 op_sel:[0,0,0] op_sel_hi:[0,1,0]
	v_fma_mix_f32 v13, v20, v89, v19 op_sel:[0,1,0] op_sel_hi:[0,1,0]
	s_waitcnt lgkmcnt(4)
	ds_read_b64 v[72:73], v6 offset:9240
	v_fma_mix_f32 v14, v10, v26, 0 op_sel:[0,0,0] op_sel_hi:[0,1,0]
	v_fma_mix_f32 v51, v10, v92, 0 op_sel:[0,0,0] op_sel_hi:[0,1,0]
	v_fma_mix_f32 v14, v11, v26, v14 op_sel:[0,1,0] op_sel_hi:[0,1,0]
	ds_read_b128 v[74:77], v6 offset:9488
	v_fma_mix_f32 v51, v11, v92, v51 op_sel:[0,1,0] op_sel_hi:[0,1,0]
	v_fma_mix_f32 v14, v12, v27, v14 op_sel:[0,0,0] op_sel_hi:[0,1,0]
	v_fma_mix_f32 v51, v12, v93, v51 op_sel:[0,0,0] op_sel_hi:[0,1,0]
	ds_read_b128 v[78:81], v6 offset:9744
	v_fma_mix_f32 v14, v13, v27, v14 op_sel:[0,1,0] op_sel_hi:[0,1,0]
	v_fma_mix_f32 v16, v10, v24, 0 op_sel:[0,0,0] op_sel_hi:[0,1,0]
	v_fma_mix_f32 v17, v11, v24, 0 op_sel:[0,1,0] op_sel_hi:[0,1,0]
	ds_read_u16 v82, v7 offset:9232
	v_add_f32_dpp v20, v14, v14 quad_perm:[1,0,3,2] row_mask:0xf bank_mask:0xf bound_ctrl:1
	v_fma_mix_f32 v51, v13, v93, v51 op_sel:[0,1,0] op_sel_hi:[0,1,0]
	v_fma_mix_f32 v18, v12, v25, 0 op_sel:[0,0,0] op_sel_hi:[0,1,0]
	v_add_f32_dpp v20, v20, v20 quad_perm:[2,3,0,1] row_mask:0xf bank_mask:0xf bound_ctrl:1
	v_fma_mix_f32 v19, v13, v25, 0 op_sel:[0,1,0] op_sel_hi:[0,1,0]
	v_fma_mix_f32 v16, v34, v30, v16 op_sel:[0,0,0] op_sel_hi:[1,1,0]
	v_add_f32_dpp v20, v20, v20 row_half_mirror row_mask:0xf bank_mask:0xf bound_ctrl:1
	v_fma_mix_f32 v17, v34, v30, v17 op_sel:[0,1,0] op_sel_hi:[1,1,0]
	v_fma_mix_f32 v18, v34, v31, v18 op_sel:[0,0,0] op_sel_hi:[1,1,0]
	v_add_f32_dpp v20, v20, v20 row_mirror row_mask:0xf bank_mask:0xf bound_ctrl:1
	v_fma_mix_f32 v19, v34, v31, v19 op_sel:[0,1,0] op_sel_hi:[1,1,0]
	v_fma_mix_f32 v10, v20, v28, v16 op_sel:[0,0,0] op_sel_hi:[0,1,0]
	v_fma_mix_f32 v11, v20, v28, v17 op_sel:[0,1,0] op_sel_hi:[0,1,0]
	v_fma_mix_f32 v12, v20, v29, v18 op_sel:[0,0,0] op_sel_hi:[0,1,0]
	v_fma_mix_f32 v13, v20, v29, v19 op_sel:[0,1,0] op_sel_hi:[0,1,0]
	s_waitcnt lgkmcnt(4)
	ds_read_b64 v[84:85], v6 offset:8216
	v_fma_mix_f32 v14, v10, v38, 0 op_sel:[0,0,0] op_sel_hi:[0,1,0]
	v_fma_mix_f32 v52, v10, v32, 0 op_sel:[0,0,0] op_sel_hi:[0,1,0]
	v_fma_mix_f32 v14, v11, v38, v14 op_sel:[0,1,0] op_sel_hi:[0,1,0]
	ds_read_b128 v[86:89], v6 offset:8464
	v_fma_mix_f32 v52, v11, v32, v52 op_sel:[0,1,0] op_sel_hi:[0,1,0]
	v_fma_mix_f32 v14, v12, v39, v14 op_sel:[0,0,0] op_sel_hi:[0,1,0]
	v_fma_mix_f32 v52, v12, v33, v52 op_sel:[0,0,0] op_sel_hi:[0,1,0]
	ds_read_b128 v[90:93], v6 offset:8720
	v_fma_mix_f32 v14, v13, v39, v14 op_sel:[0,1,0] op_sel_hi:[0,1,0]
	v_fma_mix_f32 v16, v10, v36, 0 op_sel:[0,0,0] op_sel_hi:[0,1,0]
	v_fma_mix_f32 v17, v11, v36, 0 op_sel:[0,1,0] op_sel_hi:[0,1,0]
	ds_read_u16 v94, v7 offset:8208
	v_add_f32_dpp v20, v14, v14 quad_perm:[1,0,3,2] row_mask:0xf bank_mask:0xf bound_ctrl:1
	v_fma_mix_f32 v52, v13, v33, v52 op_sel:[0,1,0] op_sel_hi:[0,1,0]
	v_fma_mix_f32 v18, v12, v37, 0 op_sel:[0,0,0] op_sel_hi:[0,1,0]
	v_add_f32_dpp v20, v20, v20 quad_perm:[2,3,0,1] row_mask:0xf bank_mask:0xf bound_ctrl:1
	v_fma_mix_f32 v19, v13, v37, 0 op_sel:[0,1,0] op_sel_hi:[0,1,0]
	v_fma_mix_f32 v16, v46, v42, v16 op_sel:[0,0,0] op_sel_hi:[1,1,0]
	v_add_f32_dpp v20, v20, v20 row_half_mirror row_mask:0xf bank_mask:0xf bound_ctrl:1
	v_fma_mix_f32 v17, v46, v42, v17 op_sel:[0,1,0] op_sel_hi:[1,1,0]
	v_fma_mix_f32 v18, v46, v43, v18 op_sel:[0,0,0] op_sel_hi:[1,1,0]
	v_add_f32_dpp v20, v20, v20 row_mirror row_mask:0xf bank_mask:0xf bound_ctrl:1
	v_fma_mix_f32 v19, v46, v43, v19 op_sel:[0,1,0] op_sel_hi:[1,1,0]
	v_fma_mix_f32 v10, v20, v40, v16 op_sel:[0,0,0] op_sel_hi:[0,1,0]
	v_fma_mix_f32 v11, v20, v40, v17 op_sel:[0,1,0] op_sel_hi:[0,1,0]
	v_fma_mix_f32 v12, v20, v41, v18 op_sel:[0,0,0] op_sel_hi:[0,1,0]
	v_fma_mix_f32 v13, v20, v41, v19 op_sel:[0,1,0] op_sel_hi:[0,1,0]
	s_waitcnt lgkmcnt(4)
	ds_read_b64 v[24:25], v6 offset:7192
	v_fma_mix_f32 v14, v10, v74, 0 op_sel:[0,0,0] op_sel_hi:[0,1,0]
	v_fma_mix_f32 v53, v10, v44, 0 op_sel:[0,0,0] op_sel_hi:[0,1,0]
	v_fma_mix_f32 v14, v11, v74, v14 op_sel:[0,1,0] op_sel_hi:[0,1,0]
	ds_read_b128 v[26:29], v6 offset:7440
	v_fma_mix_f32 v53, v11, v44, v53 op_sel:[0,1,0] op_sel_hi:[0,1,0]
	v_fma_mix_f32 v14, v12, v75, v14 op_sel:[0,0,0] op_sel_hi:[0,1,0]
	v_fma_mix_f32 v53, v12, v45, v53 op_sel:[0,0,0] op_sel_hi:[0,1,0]
	ds_read_b128 v[30:33], v6 offset:7696
	v_fma_mix_f32 v14, v13, v75, v14 op_sel:[0,1,0] op_sel_hi:[0,1,0]
	v_fma_mix_f32 v16, v10, v72, 0 op_sel:[0,0,0] op_sel_hi:[0,1,0]
	v_fma_mix_f32 v17, v11, v72, 0 op_sel:[0,1,0] op_sel_hi:[0,1,0]
	ds_read_u16 v34, v7 offset:7184
	v_add_f32_dpp v20, v14, v14 quad_perm:[1,0,3,2] row_mask:0xf bank_mask:0xf bound_ctrl:1
	v_fma_mix_f32 v53, v13, v45, v53 op_sel:[0,1,0] op_sel_hi:[0,1,0]
	v_fma_mix_f32 v18, v12, v73, 0 op_sel:[0,0,0] op_sel_hi:[0,1,0]
	v_add_f32_dpp v20, v20, v20 quad_perm:[2,3,0,1] row_mask:0xf bank_mask:0xf bound_ctrl:1
	v_fma_mix_f32 v19, v13, v73, 0 op_sel:[0,1,0] op_sel_hi:[0,1,0]
	v_fma_mix_f32 v16, v82, v78, v16 op_sel:[0,0,0] op_sel_hi:[1,1,0]
	v_add_f32_dpp v20, v20, v20 row_half_mirror row_mask:0xf bank_mask:0xf bound_ctrl:1
	v_fma_mix_f32 v17, v82, v78, v17 op_sel:[0,1,0] op_sel_hi:[1,1,0]
	v_fma_mix_f32 v18, v82, v79, v18 op_sel:[0,0,0] op_sel_hi:[1,1,0]
	v_add_f32_dpp v20, v20, v20 row_mirror row_mask:0xf bank_mask:0xf bound_ctrl:1
	v_fma_mix_f32 v19, v82, v79, v19 op_sel:[0,1,0] op_sel_hi:[1,1,0]
	v_fma_mix_f32 v10, v20, v76, v16 op_sel:[0,0,0] op_sel_hi:[0,1,0]
	v_fma_mix_f32 v11, v20, v76, v17 op_sel:[0,1,0] op_sel_hi:[0,1,0]
	v_fma_mix_f32 v12, v20, v77, v18 op_sel:[0,0,0] op_sel_hi:[0,1,0]
	v_fma_mix_f32 v13, v20, v77, v19 op_sel:[0,1,0] op_sel_hi:[0,1,0]
	s_waitcnt lgkmcnt(4)
	ds_read_b64 v[36:37], v6 offset:6168
	v_fma_mix_f32 v14, v10, v86, 0 op_sel:[0,0,0] op_sel_hi:[0,1,0]
	v_fma_mix_f32 v54, v10, v80, 0 op_sel:[0,0,0] op_sel_hi:[0,1,0]
	v_fma_mix_f32 v14, v11, v86, v14 op_sel:[0,1,0] op_sel_hi:[0,1,0]
	ds_read_b128 v[38:41], v6 offset:6416
	v_fma_mix_f32 v54, v11, v80, v54 op_sel:[0,1,0] op_sel_hi:[0,1,0]
	v_fma_mix_f32 v14, v12, v87, v14 op_sel:[0,0,0] op_sel_hi:[0,1,0]
	v_fma_mix_f32 v54, v12, v81, v54 op_sel:[0,0,0] op_sel_hi:[0,1,0]
	ds_read_b128 v[42:45], v6 offset:6672
	v_fma_mix_f32 v14, v13, v87, v14 op_sel:[0,1,0] op_sel_hi:[0,1,0]
	v_fma_mix_f32 v16, v10, v84, 0 op_sel:[0,0,0] op_sel_hi:[0,1,0]
	v_fma_mix_f32 v17, v11, v84, 0 op_sel:[0,1,0] op_sel_hi:[0,1,0]
	ds_read_u16 v46, v7 offset:6160
	v_add_f32_dpp v20, v14, v14 quad_perm:[1,0,3,2] row_mask:0xf bank_mask:0xf bound_ctrl:1
	v_fma_mix_f32 v54, v13, v81, v54 op_sel:[0,1,0] op_sel_hi:[0,1,0]
	v_fma_mix_f32 v18, v12, v85, 0 op_sel:[0,0,0] op_sel_hi:[0,1,0]
	v_add_f32_dpp v20, v20, v20 quad_perm:[2,3,0,1] row_mask:0xf bank_mask:0xf bound_ctrl:1
	v_fma_mix_f32 v19, v13, v85, 0 op_sel:[0,1,0] op_sel_hi:[0,1,0]
	v_fma_mix_f32 v16, v94, v90, v16 op_sel:[0,0,0] op_sel_hi:[1,1,0]
	v_add_f32_dpp v20, v20, v20 row_half_mirror row_mask:0xf bank_mask:0xf bound_ctrl:1
	v_fma_mix_f32 v17, v94, v90, v17 op_sel:[0,1,0] op_sel_hi:[1,1,0]
	v_fma_mix_f32 v18, v94, v91, v18 op_sel:[0,0,0] op_sel_hi:[1,1,0]
	v_add_f32_dpp v20, v20, v20 row_mirror row_mask:0xf bank_mask:0xf bound_ctrl:1
	v_fma_mix_f32 v19, v94, v91, v19 op_sel:[0,1,0] op_sel_hi:[1,1,0]
	v_fma_mix_f32 v10, v20, v88, v16 op_sel:[0,0,0] op_sel_hi:[0,1,0]
	v_fma_mix_f32 v11, v20, v88, v17 op_sel:[0,1,0] op_sel_hi:[0,1,0]
	v_fma_mix_f32 v12, v20, v89, v18 op_sel:[0,0,0] op_sel_hi:[0,1,0]
	v_fma_mix_f32 v13, v20, v89, v19 op_sel:[0,1,0] op_sel_hi:[0,1,0]
	s_waitcnt lgkmcnt(4)
	ds_read_b64 v[72:73], v6 offset:5144
	v_fma_mix_f32 v14, v10, v26, 0 op_sel:[0,0,0] op_sel_hi:[0,1,0]
	v_fma_mix_f32 v55, v10, v92, 0 op_sel:[0,0,0] op_sel_hi:[0,1,0]
	v_fma_mix_f32 v14, v11, v26, v14 op_sel:[0,1,0] op_sel_hi:[0,1,0]
	ds_read_b128 v[74:77], v6 offset:5392
	v_fma_mix_f32 v55, v11, v92, v55 op_sel:[0,1,0] op_sel_hi:[0,1,0]
	v_fma_mix_f32 v14, v12, v27, v14 op_sel:[0,0,0] op_sel_hi:[0,1,0]
	v_fma_mix_f32 v55, v12, v93, v55 op_sel:[0,0,0] op_sel_hi:[0,1,0]
	ds_read_b128 v[78:81], v6 offset:5648
	v_fma_mix_f32 v14, v13, v27, v14 op_sel:[0,1,0] op_sel_hi:[0,1,0]
	v_fma_mix_f32 v16, v10, v24, 0 op_sel:[0,0,0] op_sel_hi:[0,1,0]
	v_fma_mix_f32 v17, v11, v24, 0 op_sel:[0,1,0] op_sel_hi:[0,1,0]
	ds_read_u16 v82, v7 offset:5136
	v_add_f32_dpp v20, v14, v14 quad_perm:[1,0,3,2] row_mask:0xf bank_mask:0xf bound_ctrl:1
	v_fma_mix_f32 v55, v13, v93, v55 op_sel:[0,1,0] op_sel_hi:[0,1,0]
	v_fma_mix_f32 v18, v12, v25, 0 op_sel:[0,0,0] op_sel_hi:[0,1,0]
	v_add_f32_dpp v20, v20, v20 quad_perm:[2,3,0,1] row_mask:0xf bank_mask:0xf bound_ctrl:1
	v_fma_mix_f32 v19, v13, v25, 0 op_sel:[0,1,0] op_sel_hi:[0,1,0]
	v_fma_mix_f32 v16, v34, v30, v16 op_sel:[0,0,0] op_sel_hi:[1,1,0]
	v_add_f32_dpp v20, v20, v20 row_half_mirror row_mask:0xf bank_mask:0xf bound_ctrl:1
	v_fma_mix_f32 v17, v34, v30, v17 op_sel:[0,1,0] op_sel_hi:[1,1,0]
	v_fma_mix_f32 v18, v34, v31, v18 op_sel:[0,0,0] op_sel_hi:[1,1,0]
	v_add_f32_dpp v20, v20, v20 row_mirror row_mask:0xf bank_mask:0xf bound_ctrl:1
	v_fma_mix_f32 v19, v34, v31, v19 op_sel:[0,1,0] op_sel_hi:[1,1,0]
	v_fma_mix_f32 v10, v20, v28, v16 op_sel:[0,0,0] op_sel_hi:[0,1,0]
	v_fma_mix_f32 v11, v20, v28, v17 op_sel:[0,1,0] op_sel_hi:[0,1,0]
	v_fma_mix_f32 v12, v20, v29, v18 op_sel:[0,0,0] op_sel_hi:[0,1,0]
	v_fma_mix_f32 v13, v20, v29, v19 op_sel:[0,1,0] op_sel_hi:[0,1,0]
	s_waitcnt lgkmcnt(4)
	ds_read_b64 v[84:85], v6 offset:4120
	v_fma_mix_f32 v14, v10, v38, 0 op_sel:[0,0,0] op_sel_hi:[0,1,0]
	v_fma_mix_f32 v56, v10, v32, 0 op_sel:[0,0,0] op_sel_hi:[0,1,0]
	v_fma_mix_f32 v14, v11, v38, v14 op_sel:[0,1,0] op_sel_hi:[0,1,0]
	ds_read_b128 v[86:89], v6 offset:4368
	v_fma_mix_f32 v56, v11, v32, v56 op_sel:[0,1,0] op_sel_hi:[0,1,0]
	v_fma_mix_f32 v14, v12, v39, v14 op_sel:[0,0,0] op_sel_hi:[0,1,0]
	v_fma_mix_f32 v56, v12, v33, v56 op_sel:[0,0,0] op_sel_hi:[0,1,0]
	ds_read_b128 v[90:93], v6 offset:4624
	v_fma_mix_f32 v14, v13, v39, v14 op_sel:[0,1,0] op_sel_hi:[0,1,0]
	v_fma_mix_f32 v16, v10, v36, 0 op_sel:[0,0,0] op_sel_hi:[0,1,0]
	v_fma_mix_f32 v17, v11, v36, 0 op_sel:[0,1,0] op_sel_hi:[0,1,0]
	ds_read_u16 v94, v7 offset:4112
	v_add_f32_dpp v20, v14, v14 quad_perm:[1,0,3,2] row_mask:0xf bank_mask:0xf bound_ctrl:1
	v_fma_mix_f32 v56, v13, v33, v56 op_sel:[0,1,0] op_sel_hi:[0,1,0]
	v_fma_mix_f32 v18, v12, v37, 0 op_sel:[0,0,0] op_sel_hi:[0,1,0]
	v_add_f32_dpp v20, v20, v20 quad_perm:[2,3,0,1] row_mask:0xf bank_mask:0xf bound_ctrl:1
	v_fma_mix_f32 v19, v13, v37, 0 op_sel:[0,1,0] op_sel_hi:[0,1,0]
	v_fma_mix_f32 v16, v46, v42, v16 op_sel:[0,0,0] op_sel_hi:[1,1,0]
	v_add_f32_dpp v20, v20, v20 row_half_mirror row_mask:0xf bank_mask:0xf bound_ctrl:1
	v_fma_mix_f32 v17, v46, v42, v17 op_sel:[0,1,0] op_sel_hi:[1,1,0]
	v_fma_mix_f32 v18, v46, v43, v18 op_sel:[0,0,0] op_sel_hi:[1,1,0]
	v_add_f32_dpp v20, v20, v20 row_mirror row_mask:0xf bank_mask:0xf bound_ctrl:1
	v_fma_mix_f32 v19, v46, v43, v19 op_sel:[0,1,0] op_sel_hi:[1,1,0]
	v_fma_mix_f32 v10, v20, v40, v16 op_sel:[0,0,0] op_sel_hi:[0,1,0]
	v_fma_mix_f32 v11, v20, v40, v17 op_sel:[0,1,0] op_sel_hi:[0,1,0]
	v_fma_mix_f32 v12, v20, v41, v18 op_sel:[0,0,0] op_sel_hi:[0,1,0]
	v_fma_mix_f32 v13, v20, v41, v19 op_sel:[0,1,0] op_sel_hi:[0,1,0]
	s_waitcnt lgkmcnt(4)
	ds_read_b64 v[24:25], v6 offset:3096
	v_fma_mix_f32 v14, v10, v74, 0 op_sel:[0,0,0] op_sel_hi:[0,1,0]
	v_fma_mix_f32 v57, v10, v44, 0 op_sel:[0,0,0] op_sel_hi:[0,1,0]
	v_fma_mix_f32 v14, v11, v74, v14 op_sel:[0,1,0] op_sel_hi:[0,1,0]
	ds_read_b128 v[26:29], v6 offset:3344
	v_fma_mix_f32 v57, v11, v44, v57 op_sel:[0,1,0] op_sel_hi:[0,1,0]
	v_fma_mix_f32 v14, v12, v75, v14 op_sel:[0,0,0] op_sel_hi:[0,1,0]
	v_fma_mix_f32 v57, v12, v45, v57 op_sel:[0,0,0] op_sel_hi:[0,1,0]
	ds_read_b128 v[30:33], v6 offset:3600
	v_fma_mix_f32 v14, v13, v75, v14 op_sel:[0,1,0] op_sel_hi:[0,1,0]
	v_fma_mix_f32 v16, v10, v72, 0 op_sel:[0,0,0] op_sel_hi:[0,1,0]
	v_fma_mix_f32 v17, v11, v72, 0 op_sel:[0,1,0] op_sel_hi:[0,1,0]
	ds_read_u16 v34, v7 offset:3088
	v_add_f32_dpp v20, v14, v14 quad_perm:[1,0,3,2] row_mask:0xf bank_mask:0xf bound_ctrl:1
	v_fma_mix_f32 v57, v13, v45, v57 op_sel:[0,1,0] op_sel_hi:[0,1,0]
	v_fma_mix_f32 v18, v12, v73, 0 op_sel:[0,0,0] op_sel_hi:[0,1,0]
	v_add_f32_dpp v20, v20, v20 quad_perm:[2,3,0,1] row_mask:0xf bank_mask:0xf bound_ctrl:1
	v_fma_mix_f32 v19, v13, v73, 0 op_sel:[0,1,0] op_sel_hi:[0,1,0]
	v_fma_mix_f32 v16, v82, v78, v16 op_sel:[0,0,0] op_sel_hi:[1,1,0]
	v_add_f32_dpp v20, v20, v20 row_half_mirror row_mask:0xf bank_mask:0xf bound_ctrl:1
	v_fma_mix_f32 v17, v82, v78, v17 op_sel:[0,1,0] op_sel_hi:[1,1,0]
	v_fma_mix_f32 v18, v82, v79, v18 op_sel:[0,0,0] op_sel_hi:[1,1,0]
	v_add_f32_dpp v20, v20, v20 row_mirror row_mask:0xf bank_mask:0xf bound_ctrl:1
	v_fma_mix_f32 v19, v82, v79, v19 op_sel:[0,1,0] op_sel_hi:[1,1,0]
	v_fma_mix_f32 v10, v20, v76, v16 op_sel:[0,0,0] op_sel_hi:[0,1,0]
	v_fma_mix_f32 v11, v20, v76, v17 op_sel:[0,1,0] op_sel_hi:[0,1,0]
	v_fma_mix_f32 v12, v20, v77, v18 op_sel:[0,0,0] op_sel_hi:[0,1,0]
	v_fma_mix_f32 v13, v20, v77, v19 op_sel:[0,1,0] op_sel_hi:[0,1,0]
	s_waitcnt lgkmcnt(4)
	ds_read_b64 v[36:37], v6 offset:2072
	v_fma_mix_f32 v14, v10, v86, 0 op_sel:[0,0,0] op_sel_hi:[0,1,0]
	v_fma_mix_f32 v58, v10, v80, 0 op_sel:[0,0,0] op_sel_hi:[0,1,0]
	v_fma_mix_f32 v14, v11, v86, v14 op_sel:[0,1,0] op_sel_hi:[0,1,0]
	ds_read_b128 v[38:41], v6 offset:2320
	v_fma_mix_f32 v58, v11, v80, v58 op_sel:[0,1,0] op_sel_hi:[0,1,0]
	v_fma_mix_f32 v14, v12, v87, v14 op_sel:[0,0,0] op_sel_hi:[0,1,0]
	v_fma_mix_f32 v58, v12, v81, v58 op_sel:[0,0,0] op_sel_hi:[0,1,0]
	ds_read_b128 v[42:45], v6 offset:2576
	v_fma_mix_f32 v14, v13, v87, v14 op_sel:[0,1,0] op_sel_hi:[0,1,0]
	v_fma_mix_f32 v16, v10, v84, 0 op_sel:[0,0,0] op_sel_hi:[0,1,0]
	v_fma_mix_f32 v17, v11, v84, 0 op_sel:[0,1,0] op_sel_hi:[0,1,0]
	ds_read_u16 v46, v7 offset:2064
	v_add_f32_dpp v20, v14, v14 quad_perm:[1,0,3,2] row_mask:0xf bank_mask:0xf bound_ctrl:1
	v_fma_mix_f32 v58, v13, v81, v58 op_sel:[0,1,0] op_sel_hi:[0,1,0]
	v_fma_mix_f32 v18, v12, v85, 0 op_sel:[0,0,0] op_sel_hi:[0,1,0]
	v_add_f32_dpp v20, v20, v20 quad_perm:[2,3,0,1] row_mask:0xf bank_mask:0xf bound_ctrl:1
	v_fma_mix_f32 v19, v13, v85, 0 op_sel:[0,1,0] op_sel_hi:[0,1,0]
	v_fma_mix_f32 v16, v94, v90, v16 op_sel:[0,0,0] op_sel_hi:[1,1,0]
	v_add_f32_dpp v20, v20, v20 row_half_mirror row_mask:0xf bank_mask:0xf bound_ctrl:1
	v_fma_mix_f32 v17, v94, v90, v17 op_sel:[0,1,0] op_sel_hi:[1,1,0]
	v_fma_mix_f32 v18, v94, v91, v18 op_sel:[0,0,0] op_sel_hi:[1,1,0]
	v_add_f32_dpp v20, v20, v20 row_mirror row_mask:0xf bank_mask:0xf bound_ctrl:1
	v_fma_mix_f32 v19, v94, v91, v19 op_sel:[0,1,0] op_sel_hi:[1,1,0]
	v_fma_mix_f32 v10, v20, v88, v16 op_sel:[0,0,0] op_sel_hi:[0,1,0]
	v_fma_mix_f32 v11, v20, v88, v17 op_sel:[0,1,0] op_sel_hi:[0,1,0]
	v_fma_mix_f32 v12, v20, v89, v18 op_sel:[0,0,0] op_sel_hi:[0,1,0]
	v_fma_mix_f32 v13, v20, v89, v19 op_sel:[0,1,0] op_sel_hi:[0,1,0]
	s_waitcnt lgkmcnt(4)
	ds_read_b64 v[72:73], v6 offset:1048
	v_fma_mix_f32 v14, v10, v26, 0 op_sel:[0,0,0] op_sel_hi:[0,1,0]
	v_fma_mix_f32 v59, v10, v92, 0 op_sel:[0,0,0] op_sel_hi:[0,1,0]
	v_fma_mix_f32 v14, v11, v26, v14 op_sel:[0,1,0] op_sel_hi:[0,1,0]
	ds_read_b128 v[74:77], v6 offset:1296
	v_fma_mix_f32 v59, v11, v92, v59 op_sel:[0,1,0] op_sel_hi:[0,1,0]
	v_fma_mix_f32 v14, v12, v27, v14 op_sel:[0,0,0] op_sel_hi:[0,1,0]
	v_fma_mix_f32 v59, v12, v93, v59 op_sel:[0,0,0] op_sel_hi:[0,1,0]
	ds_read_b128 v[78:81], v6 offset:1552
	v_fma_mix_f32 v14, v13, v27, v14 op_sel:[0,1,0] op_sel_hi:[0,1,0]
	v_fma_mix_f32 v16, v10, v24, 0 op_sel:[0,0,0] op_sel_hi:[0,1,0]
	v_fma_mix_f32 v17, v11, v24, 0 op_sel:[0,1,0] op_sel_hi:[0,1,0]
	ds_read_u16 v82, v7 offset:1040
	v_add_f32_dpp v20, v14, v14 quad_perm:[1,0,3,2] row_mask:0xf bank_mask:0xf bound_ctrl:1
	v_fma_mix_f32 v59, v13, v93, v59 op_sel:[0,1,0] op_sel_hi:[0,1,0]
	v_fma_mix_f32 v18, v12, v25, 0 op_sel:[0,0,0] op_sel_hi:[0,1,0]
	v_add_f32_dpp v20, v20, v20 quad_perm:[2,3,0,1] row_mask:0xf bank_mask:0xf bound_ctrl:1
	v_fma_mix_f32 v19, v13, v25, 0 op_sel:[0,1,0] op_sel_hi:[0,1,0]
	v_fma_mix_f32 v16, v34, v30, v16 op_sel:[0,0,0] op_sel_hi:[1,1,0]
	v_add_f32_dpp v20, v20, v20 row_half_mirror row_mask:0xf bank_mask:0xf bound_ctrl:1
	v_fma_mix_f32 v17, v34, v30, v17 op_sel:[0,1,0] op_sel_hi:[1,1,0]
	v_fma_mix_f32 v18, v34, v31, v18 op_sel:[0,0,0] op_sel_hi:[1,1,0]
	v_add_f32_dpp v20, v20, v20 row_mirror row_mask:0xf bank_mask:0xf bound_ctrl:1
	v_fma_mix_f32 v19, v34, v31, v19 op_sel:[0,1,0] op_sel_hi:[1,1,0]
	v_fma_mix_f32 v10, v20, v28, v16 op_sel:[0,0,0] op_sel_hi:[0,1,0]
	v_fma_mix_f32 v11, v20, v28, v17 op_sel:[0,1,0] op_sel_hi:[0,1,0]
	v_fma_mix_f32 v12, v20, v29, v18 op_sel:[0,0,0] op_sel_hi:[0,1,0]
	v_fma_mix_f32 v13, v20, v29, v19 op_sel:[0,1,0] op_sel_hi:[0,1,0]
	s_waitcnt lgkmcnt(4)
; DEVINL u16 f2bf(float a) { return (u16)(pk2(a, 0.f) & 0xffffu); }
; #define RW_STEP2(B) RW_STEP(B, WvA, XA, KrA, vhA, WvB, XB, KrB, vhB); RW_STEP((B) + 1, WvB, XB, KrB, vhB, WvA, XA, KrA, vhA)
; #define RW_STEP4(B) RW_STEP2(B); RW_STEP2((B) + 2)
; template <int DIR>
; DEVINL void rwkv_scan_dir(const Params& p, int task, int lane, int wave) {
;     ...
;   for (int st = 0; st < 4096; st += 32) {
;     RW_STEP(0, WvA, XA, KrA, vhA, WvB, XB, KrB, vhB);
;     if (st > 0) { const int q0 = st - 16 + seg; yo[(long)(DIR ? (4095 - q0) : q0) * 1024] = f2bf(ykeep); }
;     RW_STEP(1, WvB, XB, KrB, vhB, WvA, XA, KrA, vhA);
;     RW_STEP2(2); RW_STEP4(4); RW_STEP4(8); RW_STEP4(12);
;     RW_STEP(16, WvA, XA, KrA, vhA, WvB, XB, KrB, vhB);
;     { const int q0 = st + seg; yo[(long)(DIR ? (4095 - q0) : q0) * 1024] = f2bf(ykeep); }
;     RW_STEP(17, WvB, XB, KrB, vhB, WvA, XA, KrA, vhA);
;     RW_STEP2(18); RW_STEP4(20); RW_STEP4(24); RW_STEP4(28);
;   }
	ds_read_b128 v[100:103], v9
	ds_read_b128 v[104:107], v9 offset:16
	ds_read_b64 v[84:85], v6 offset:24
	v_fma_mix_f32 v14, v10, v38, 0 op_sel:[0,0,0] op_sel_hi:[0,1,0]
	v_fma_mix_f32 v60, v10, v32, 0 op_sel:[0,0,0] op_sel_hi:[0,1,0]
	v_fma_mix_f32 v14, v11, v38, v14 op_sel:[0,1,0] op_sel_hi:[0,1,0]
	ds_read_b128 v[86:89], v6 offset:272
	v_fma_mix_f32 v60, v11, v32, v60 op_sel:[0,1,0] op_sel_hi:[0,1,0]
	v_fma_mix_f32 v14, v12, v39, v14 op_sel:[0,0,0] op_sel_hi:[0,1,0]
	v_fma_mix_f32 v60, v12, v33, v60 op_sel:[0,0,0] op_sel_hi:[0,1,0]
	ds_read_b128 v[90:93], v6 offset:528
	v_fma_mix_f32 v14, v13, v39, v14 op_sel:[0,1,0] op_sel_hi:[0,1,0]
	v_fma_mix_f32 v16, v10, v36, 0 op_sel:[0,0,0] op_sel_hi:[0,1,0]
	v_fma_mix_f32 v17, v11, v36, 0 op_sel:[0,1,0] op_sel_hi:[0,1,0]
	ds_read_u16 v94, v7 offset:16
	v_add_f32_dpp v20, v14, v14 quad_perm:[1,0,3,2] row_mask:0xf bank_mask:0xf bound_ctrl:1
	v_fma_mix_f32 v60, v13, v33, v60 op_sel:[0,1,0] op_sel_hi:[0,1,0]
	v_fma_mix_f32 v18, v12, v37, 0 op_sel:[0,0,0] op_sel_hi:[0,1,0]
	v_add_f32_dpp v20, v20, v20 quad_perm:[2,3,0,1] row_mask:0xf bank_mask:0xf bound_ctrl:1
	v_fma_mix_f32 v19, v13, v37, 0 op_sel:[0,1,0] op_sel_hi:[0,1,0]
	v_fma_mix_f32 v16, v46, v42, v16 op_sel:[0,0,0] op_sel_hi:[1,1,0]
	v_add_f32_dpp v20, v20, v20 row_half_mirror row_mask:0xf bank_mask:0xf bound_ctrl:1
	v_fma_mix_f32 v17, v46, v42, v17 op_sel:[0,1,0] op_sel_hi:[1,1,0]
	v_fma_mix_f32 v18, v46, v43, v18 op_sel:[0,0,0] op_sel_hi:[1,1,0]
	v_add_f32_dpp v20, v20, v20 row_mirror row_mask:0xf bank_mask:0xf bound_ctrl:1
	v_fma_mix_f32 v19, v46, v43, v19 op_sel:[0,1,0] op_sel_hi:[1,1,0]
	v_fma_mix_f32 v10, v20, v40, v16 op_sel:[0,0,0] op_sel_hi:[0,1,0]
	v_fma_mix_f32 v11, v20, v40, v17 op_sel:[0,1,0] op_sel_hi:[0,1,0]
	v_fma_mix_f32 v12, v20, v41, v18 op_sel:[0,0,0] op_sel_hi:[0,1,0]
	v_fma_mix_f32 v13, v20, v41, v19 op_sel:[0,1,0] op_sel_hi:[0,1,0]
	s_waitcnt lgkmcnt(4)
	v_add_u32_e32 v6, 0xffffc000, v6
	v_add_u32_e32 v7, 0xffffc000, v7
	v_and_b32_e32 v6, 0x1ffff, v6
	v_and_b32_e32 v7, 0x1ffff, v7
	ds_read_b64 v[24:25], v6 offset:15384
	v_fma_mix_f32 v14, v10, v74, 0 op_sel:[0,0,0] op_sel_hi:[0,1,0]
	v_fma_mix_f32 v61, v10, v44, 0 op_sel:[0,0,0] op_sel_hi:[0,1,0]
	v_fma_mix_f32 v14, v11, v74, v14 op_sel:[0,1,0] op_sel_hi:[0,1,0]
	ds_read_b128 v[26:29], v6 offset:15632
	v_fma_mix_f32 v61, v11, v44, v61 op_sel:[0,1,0] op_sel_hi:[0,1,0]
	v_fma_mix_f32 v14, v12, v75, v14 op_sel:[0,0,0] op_sel_hi:[0,1,0]
	v_fma_mix_f32 v61, v12, v45, v61 op_sel:[0,0,0] op_sel_hi:[0,1,0]
	ds_read_b128 v[30:33], v6 offset:15888
	v_fma_mix_f32 v14, v13, v75, v14 op_sel:[0,1,0] op_sel_hi:[0,1,0]
	v_fma_mix_f32 v16, v10, v72, 0 op_sel:[0,0,0] op_sel_hi:[0,1,0]
	v_fma_mix_f32 v17, v11, v72, 0 op_sel:[0,1,0] op_sel_hi:[0,1,0]
	ds_read_u16 v34, v7 offset:15376
	v_add_f32_dpp v20, v14, v14 quad_perm:[1,0,3,2] row_mask:0xf bank_mask:0xf bound_ctrl:1
	v_fma_mix_f32 v61, v13, v45, v61 op_sel:[0,1,0] op_sel_hi:[0,1,0]
	v_fma_mix_f32 v18, v12, v73, 0 op_sel:[0,0,0] op_sel_hi:[0,1,0]
	v_add_f32_dpp v20, v20, v20 quad_perm:[2,3,0,1] row_mask:0xf bank_mask:0xf bound_ctrl:1
	v_fma_mix_f32 v19, v13, v73, 0 op_sel:[0,1,0] op_sel_hi:[0,1,0]
	v_fma_mix_f32 v16, v82, v78, v16 op_sel:[0,0,0] op_sel_hi:[1,1,0]
	v_add_f32_dpp v20, v20, v20 row_half_mirror row_mask:0xf bank_mask:0xf bound_ctrl:1
	v_fma_mix_f32 v17, v82, v78, v17 op_sel:[0,1,0] op_sel_hi:[1,1,0]
	v_fma_mix_f32 v18, v82, v79, v18 op_sel:[0,0,0] op_sel_hi:[1,1,0]
	v_add_f32_dpp v20, v20, v20 row_mirror row_mask:0xf bank_mask:0xf bound_ctrl:1
	v_fma_mix_f32 v19, v82, v79, v19 op_sel:[0,1,0] op_sel_hi:[1,1,0]
	v_fma_mix_f32 v10, v20, v76, v16 op_sel:[0,0,0] op_sel_hi:[0,1,0]
	v_fma_mix_f32 v11, v20, v76, v17 op_sel:[0,1,0] op_sel_hi:[0,1,0]
	v_fma_mix_f32 v12, v20, v77, v18 op_sel:[0,0,0] op_sel_hi:[0,1,0]
	v_fma_mix_f32 v13, v20, v77, v19 op_sel:[0,1,0] op_sel_hi:[0,1,0]
	s_waitcnt lgkmcnt(4)
	ds_read_b64 v[36:37], v6 offset:14360
	v_fma_mix_f32 v14, v10, v86, 0 op_sel:[0,0,0] op_sel_hi:[0,1,0]
	v_fma_mix_f32 v62, v10, v80, 0 op_sel:[0,0,0] op_sel_hi:[0,1,0]
	v_fma_mix_f32 v14, v11, v86, v14 op_sel:[0,1,0] op_sel_hi:[0,1,0]
	ds_read_b128 v[38:41], v6 offset:14608
	v_fma_mix_f32 v62, v11, v80, v62 op_sel:[0,1,0] op_sel_hi:[0,1,0]
	v_fma_mix_f32 v14, v12, v87, v14 op_sel:[0,0,0] op_sel_hi:[0,1,0]
	v_fma_mix_f32 v62, v12, v81, v62 op_sel:[0,0,0] op_sel_hi:[0,1,0]
	ds_read_b128 v[42:45], v6 offset:14864
	v_fma_mix_f32 v14, v13, v87, v14 op_sel:[0,1,0] op_sel_hi:[0,1,0]
	v_fma_mix_f32 v16, v10, v84, 0 op_sel:[0,0,0] op_sel_hi:[0,1,0]
	v_fma_mix_f32 v17, v11, v84, 0 op_sel:[0,1,0] op_sel_hi:[0,1,0]
	ds_read_u16 v46, v7 offset:14352
	v_add_f32_dpp v20, v14, v14 quad_perm:[1,0,3,2] row_mask:0xf bank_mask:0xf bound_ctrl:1
	v_fma_mix_f32 v62, v13, v81, v62 op_sel:[0,1,0] op_sel_hi:[0,1,0]
	v_fma_mix_f32 v18, v12, v85, 0 op_sel:[0,0,0] op_sel_hi:[0,1,0]
	v_add_f32_dpp v20, v20, v20 quad_perm:[2,3,0,1] row_mask:0xf bank_mask:0xf bound_ctrl:1
	v_fma_mix_f32 v19, v13, v85, 0 op_sel:[0,1,0] op_sel_hi:[0,1,0]
	v_fma_mix_f32 v16, v94, v90, v16 op_sel:[0,0,0] op_sel_hi:[1,1,0]
	v_add_f32_dpp v20, v20, v20 row_half_mirror row_mask:0xf bank_mask:0xf bound_ctrl:1
	v_fma_mix_f32 v17, v94, v90, v17 op_sel:[0,1,0] op_sel_hi:[1,1,0]
	v_fma_mix_f32 v18, v94, v91, v18 op_sel:[0,0,0] op_sel_hi:[1,1,0]
	v_add_f32_dpp v20, v20, v20 row_mirror row_mask:0xf bank_mask:0xf bound_ctrl:1
	v_fma_mix_f32 v19, v94, v91, v19 op_sel:[0,1,0] op_sel_hi:[1,1,0]
	v_fma_mix_f32 v10, v20, v88, v16 op_sel:[0,0,0] op_sel_hi:[0,1,0]
	v_fma_mix_f32 v11, v20, v88, v17 op_sel:[0,1,0] op_sel_hi:[0,1,0]
	v_fma_mix_f32 v12, v20, v89, v18 op_sel:[0,0,0] op_sel_hi:[0,1,0]
	v_fma_mix_f32 v13, v20, v89, v19 op_sel:[0,1,0] op_sel_hi:[0,1,0]
	s_waitcnt lgkmcnt(4)
	s_add_u32 s15, s15, 1
	s_add_u32 s14, s14, 1
	v_mov_b32_e32 v69, s15
	ds_write_b32 v68, v69
	s_cmp_lt_u32 s14, 0x100
	s_cbranch_scc1 .Lrw_blk_d1
; DEVINL u16 f2bf(float a) { return (u16)(pk2(a, 0.f) & 0xffffu); }
; template <int DIR>
; DEVINL void rwkv_scan_dir(const Params& p, int task, int lane, int wave) {
;     ...
;   {
;     const float ylast = allred16(ypart);
;     ykeep = (seg == 15) ? ylast : ykeep;
;     const int q0 = 4096 - 16 + seg; yo[(long)(DIR ? (4095 - q0) : q0) * 1024] = f2bf(ykeep);
;   }
;   asm volatile("s_waitcnt vmcnt(0)" ::: "memory");
	v_fma_mix_f32 v21, v10, v92, 0 op_sel:[0,0,0] op_sel_hi:[0,1,0]
	v_fma_mix_f32 v22, v12, v93, 0 op_sel:[0,0,0] op_sel_hi:[0,1,0]
	v_fma_mix_f32 v21, v11, v92, v21 op_sel:[0,1,0] op_sel_hi:[0,1,0]
	v_fma_mix_f32 v22, v13, v93, v22 op_sel:[0,1,0] op_sel_hi:[0,1,0]
	v_add_f32_e32 v63, v21, v22
	s_nop 1
	v_add_f32_dpp v48, v48, v48 row_ror:8 row_mask:0xf bank_mask:0x3
	v_add_f32_dpp v49, v49, v49 row_ror:8 row_mask:0xf bank_mask:0x3
	v_add_f32_dpp v50, v50, v50 row_ror:8 row_mask:0xf bank_mask:0x3
	v_add_f32_dpp v51, v51, v51 row_ror:8 row_mask:0xf bank_mask:0x3
	v_add_f32_dpp v52, v52, v52 row_ror:8 row_mask:0xf bank_mask:0x3
	v_add_f32_dpp v53, v53, v53 row_ror:8 row_mask:0xf bank_mask:0x3
	v_add_f32_dpp v54, v54, v54 row_ror:8 row_mask:0xf bank_mask:0x3
	v_add_f32_dpp v55, v55, v55 row_ror:8 row_mask:0xf bank_mask:0x3
	v_add_f32_dpp v48, v56, v56 row_ror:8 row_mask:0xf bank_mask:0xc
	v_add_f32_dpp v49, v57, v57 row_ror:8 row_mask:0xf bank_mask:0xc
	v_add_f32_dpp v50, v58, v58 row_ror:8 row_mask:0xf bank_mask:0xc
	v_add_f32_dpp v51, v59, v59 row_ror:8 row_mask:0xf bank_mask:0xc
	v_add_f32_dpp v52, v60, v60 row_ror:8 row_mask:0xf bank_mask:0xc
	v_add_f32_dpp v53, v61, v61 row_ror:8 row_mask:0xf bank_mask:0xc
	v_add_f32_dpp v54, v62, v62 row_ror:8 row_mask:0xf bank_mask:0xc
	v_add_f32_dpp v55, v63, v63 row_ror:8 row_mask:0xf bank_mask:0xc
	v_add_f32_dpp v48, v48, v48 row_ror:12 row_mask:0xf bank_mask:0x5
	v_add_f32_dpp v49, v49, v49 row_ror:12 row_mask:0xf bank_mask:0x5
	v_add_f32_dpp v50, v50, v50 row_ror:12 row_mask:0xf bank_mask:0x5
	v_add_f32_dpp v51, v51, v51 row_ror:12 row_mask:0xf bank_mask:0x5
	v_add_f32_dpp v48, v52, v52 row_ror:4 row_mask:0xf bank_mask:0xa
	v_add_f32_dpp v49, v53, v53 row_ror:4 row_mask:0xf bank_mask:0xa
	v_add_f32_dpp v50, v54, v54 row_ror:4 row_mask:0xf bank_mask:0xa
	v_add_f32_dpp v51, v55, v55 row_ror:4 row_mask:0xf bank_mask:0xa
	v_add_f32_dpp v64, v48, v48 quad_perm:[2,3,0,1] row_mask:0xf bank_mask:0xf bound_ctrl:1
	v_add_f32_dpp v65, v50, v50 quad_perm:[2,3,0,1] row_mask:0xf bank_mask:0xf bound_ctrl:1
	v_cndmask_b32_e64 v56, v64, v65, s[50:51]
	v_add_f32_dpp v64, v49, v49 quad_perm:[2,3,0,1] row_mask:0xf bank_mask:0xf bound_ctrl:1
	v_add_f32_dpp v65, v51, v51 quad_perm:[2,3,0,1] row_mask:0xf bank_mask:0xf bound_ctrl:1
	v_cndmask_b32_e64 v57, v64, v65, s[50:51]
	v_add_f32_dpp v64, v56, v56 quad_perm:[1,0,3,2] row_mask:0xf bank_mask:0xf bound_ctrl:1
	s_nop 0
	v_add_f32_dpp v65, v57, v57 quad_perm:[1,0,3,2] row_mask:0xf bank_mask:0xf bound_ctrl:1
	v_cndmask_b32_e64 v66, v64, v65, s[48:49]
	v_cvt_pk_bf16_f32 v66, v66, v66
	global_store_short v8, v66, s[12:13]
	s_sub_u32 s12, s12, 0x8000
	s_subb_u32 s13, s13, 0
